# GEMM main loops: removed the duplicate s_waitcnt lgkmcnt(0) that followed each inline-asm wait
# speedup vs baseline: 1.0247x; 1.0031x over previous
.LBB0_100:
	s_add_u32 s21, s48, 0xfff00080
	s_addc_u32 s28, s49, -1
	s_add_i32 s60, 0, 0x10000
	v_add_u32_e32 v124, s60, v175
	ds_read_b128 v[112:115], v124
	ds_read_b128 v[116:119], v124 offset:1024
	ds_read_b128 v[120:123], v124 offset:2048
	ds_read_b128 v[124:127], v124 offset:3072
	s_cmp_eq_u32 s20, 60
	s_cselect_b32 s51, s43, s28
	s_cselect_b32 s50, s24, s21
	s_cselect_b32 s29, s1, vcc_hi
	s_cselect_b32 s28, s25, vcc_lo
	v_lshl_add_u64 v[184:185], s[48:49], 0, v[158:159]
	s_add_i32 m0, s55, 0xc000
	ds_read_b128 v[128:131], v199
	ds_read_b128 v[132:135], v199 offset:1024
	ds_read_b128 v[162:165], v199 offset:2048
	ds_read_b128 v[166:169], v199 offset:3072
	ds_read_b128 v[170:173], v199 offset:4096
	ds_read_b128 v[200:203], v199 offset:5120
	ds_read_b128 v[204:207], v199 offset:6144
	ds_read_b128 v[208:211], v199 offset:7168
	global_load_lds_dwordx4 v[184:185], off
	v_lshl_add_u64 v[184:185], s[48:49], 0, v[160:161]
	s_add_i32 m0, s55, 0xe000
	s_nop 0
	global_load_lds_dwordx4 v[184:185], off
	s_waitcnt lgkmcnt(8)
	s_barrier
	s_waitcnt lgkmcnt(0)
	v_mfma_f32_16x16x32_bf16 v[148:151], v[112:115], v[128:131], v[148:151]
	v_mfma_f32_16x16x32_bf16 v[144:147], v[120:123], v[128:131], v[144:147]
	v_mfma_f32_16x16x32_bf16 v[108:111], v[112:115], v[162:165], v[108:111]
	v_mfma_f32_16x16x32_bf16 v[104:107], v[120:123], v[162:165], v[104:107]
	v_mfma_f32_16x16x32_bf16 v[92:95], v[112:115], v[170:173], v[92:95]
	v_mfma_f32_16x16x32_bf16 v[88:91], v[120:123], v[170:173], v[88:91]
	v_mfma_f32_16x16x32_bf16 v[76:79], v[112:115], v[204:207], v[76:79]
	v_mfma_f32_16x16x32_bf16 v[72:75], v[120:123], v[204:207], v[72:75]
	v_mfma_f32_16x16x32_bf16 v[148:151], v[116:119], v[132:135], v[148:151]
	v_mfma_f32_16x16x32_bf16 v[144:147], v[124:127], v[132:135], v[144:147]
	v_mfma_f32_16x16x32_bf16 v[108:111], v[116:119], v[166:169], v[108:111]
	v_mfma_f32_16x16x32_bf16 v[104:107], v[124:127], v[166:169], v[104:107]
	v_mfma_f32_16x16x32_bf16 v[92:95], v[116:119], v[200:203], v[92:95]
	v_mfma_f32_16x16x32_bf16 v[88:91], v[124:127], v[200:203], v[88:91]
	v_mfma_f32_16x16x32_bf16 v[76:79], v[116:119], v[208:211], v[76:79]
	v_mfma_f32_16x16x32_bf16 v[72:75], v[124:127], v[208:211], v[72:75]
	s_barrier
	s_add_i32 s21, 0, 0x14000
	v_add_u32_e32 v184, s21, v175
	s_add_i32 s60, s60, s54
	ds_read_b128 v[212:215], v184
	ds_read_b128 v[216:219], v184 offset:1024
	ds_read_b128 v[232:235], v184 offset:2048
	ds_read_b128 v[236:239], v184 offset:3072
	v_lshl_add_u64 v[184:185], s[28:29], 0, v[176:177]
	s_mov_b32 m0, s60
	v_lshl_add_u64 v[192:193], s[28:29], 0, v[152:153]
	global_load_lds_dwordx4 v[184:185], off
	s_add_i32 m0, s60, 0x2000
	s_nop 0
	global_load_lds_dwordx4 v[192:193], off
	s_barrier
	s_waitcnt lgkmcnt(0)
	v_mfma_f32_16x16x32_bf16 v[140:143], v[212:215], v[128:131], v[140:143]
	v_mfma_f32_16x16x32_bf16 v[100:103], v[212:215], v[162:165], v[100:103]
	v_mfma_f32_16x16x32_bf16 v[96:99], v[232:235], v[162:165], v[96:99]
	v_mfma_f32_16x16x32_bf16 v[84:87], v[212:215], v[170:173], v[84:87]
	v_mfma_f32_16x16x32_bf16 v[80:83], v[232:235], v[170:173], v[80:83]
	v_mfma_f32_16x16x32_bf16 v[68:71], v[212:215], v[204:207], v[68:71]
	v_mfma_f32_16x16x32_bf16 v[64:67], v[232:235], v[204:207], v[64:67]
	v_mfma_f32_16x16x32_bf16 v[140:143], v[216:219], v[132:135], v[140:143]
	v_mfma_f32_16x16x32_bf16 v[128:131], v[232:235], v[128:131], v[136:139]
	v_mfma_f32_16x16x32_bf16 v[100:103], v[216:219], v[166:169], v[100:103]
	v_mfma_f32_16x16x32_bf16 v[96:99], v[236:239], v[166:169], v[96:99]
	v_mfma_f32_16x16x32_bf16 v[84:87], v[216:219], v[200:203], v[84:87]
	v_mfma_f32_16x16x32_bf16 v[80:83], v[236:239], v[200:203], v[80:83]
	v_mfma_f32_16x16x32_bf16 v[68:71], v[216:219], v[208:211], v[68:71]
	v_mfma_f32_16x16x32_bf16 v[64:67], v[236:239], v[208:211], v[64:67]
	v_mfma_f32_16x16x32_bf16 v[128:131], v[236:239], v[132:135], v[128:131]
	s_mov_b32 m0, s55
	v_lshl_add_u64 v[194:195], s[50:51], 0, v[156:157]
	s_barrier
	ds_read_b128 v[132:135], v199 offset:16384
	ds_read_b128 v[136:139], v199 offset:17408
	ds_read_b128 v[162:165], v199 offset:18432
	ds_read_b128 v[166:169], v199 offset:19456
	ds_read_b128 v[170:173], v199 offset:20480
	ds_read_b128 v[200:203], v199 offset:21504
	ds_read_b128 v[204:207], v199 offset:22528
	ds_read_b128 v[208:211], v199 offset:23552
	global_load_lds_dwordx4 v[194:195], off
	v_lshl_add_u64 v[240:241], s[50:51], 0, v[154:155]
	s_mov_b32 m0, s56
	s_nop 0
	global_load_lds_dwordx4 v[240:241], off
	s_barrier
	s_waitcnt lgkmcnt(0)
	v_mfma_f32_16x16x32_bf16 v[60:63], v[112:115], v[132:135], v[60:63]
	v_mfma_f32_16x16x32_bf16 v[56:59], v[120:123], v[132:135], v[56:59]
	v_mfma_f32_16x16x32_bf16 v[44:47], v[112:115], v[162:165], v[44:47]
	v_mfma_f32_16x16x32_bf16 v[40:43], v[120:123], v[162:165], v[40:43]
	v_mfma_f32_16x16x32_bf16 v[28:31], v[112:115], v[170:173], v[28:31]
	v_mfma_f32_16x16x32_bf16 v[24:27], v[120:123], v[170:173], v[24:27]
	v_mfma_f32_16x16x32_bf16 v[12:15], v[112:115], v[204:207], v[12:15]
	v_mfma_f32_16x16x32_bf16 v[8:11], v[120:123], v[204:207], v[8:11]
	v_mfma_f32_16x16x32_bf16 v[60:63], v[116:119], v[136:139], v[60:63]
	v_mfma_f32_16x16x32_bf16 v[56:59], v[124:127], v[136:139], v[56:59]
	v_mfma_f32_16x16x32_bf16 v[44:47], v[116:119], v[166:169], v[44:47]
	v_mfma_f32_16x16x32_bf16 v[40:43], v[124:127], v[166:169], v[40:43]
	v_mfma_f32_16x16x32_bf16 v[28:31], v[116:119], v[200:203], v[28:31]
	v_mfma_f32_16x16x32_bf16 v[24:27], v[124:127], v[200:203], v[24:27]
	v_mfma_f32_16x16x32_bf16 v[12:15], v[116:119], v[208:211], v[12:15]
	v_mfma_f32_16x16x32_bf16 v[8:11], v[124:127], v[208:211], v[8:11]
	s_barrier
	s_add_u32 s60, s28, 0x100000
	s_addc_u32 s61, s29, 0
	s_add_i32 s21, s21, s54
	v_lshl_add_u64 v[112:113], s[60:61], 0, v[176:177]
	s_mov_b32 m0, s21
	s_nop 0
	global_load_lds_dwordx4 v[112:113], off
	v_lshl_add_u64 v[112:113], s[60:61], 0, v[152:153]
	s_add_i32 m0, s21, 0x2000
	s_nop 0
	global_load_lds_dwordx4 v[112:113], off
	s_waitcnt vmcnt(6)
	s_barrier
	v_mfma_f32_16x16x32_bf16 v[52:55], v[212:215], v[132:135], v[52:55]
	v_mfma_f32_16x16x32_bf16 v[48:51], v[232:235], v[132:135], v[48:51]
	v_mfma_f32_16x16x32_bf16 v[36:39], v[212:215], v[162:165], v[36:39]
	v_mfma_f32_16x16x32_bf16 v[32:35], v[232:235], v[162:165], v[32:35]
	v_mfma_f32_16x16x32_bf16 v[20:23], v[212:215], v[170:173], v[20:23]
	v_mfma_f32_16x16x32_bf16 v[16:19], v[232:235], v[170:173], v[16:19]
	v_mfma_f32_16x16x32_bf16 v[4:7], v[212:215], v[204:207], v[4:7]
	v_mfma_f32_16x16x32_bf16 v[0:3], v[232:235], v[204:207], v[0:3]
	v_mfma_f32_16x16x32_bf16 v[52:55], v[216:219], v[136:139], v[52:55]
	v_mfma_f32_16x16x32_bf16 v[48:51], v[236:239], v[136:139], v[48:51]
	v_mfma_f32_16x16x32_bf16 v[36:39], v[216:219], v[166:169], v[36:39]
	v_mfma_f32_16x16x32_bf16 v[32:35], v[236:239], v[166:169], v[32:35]
	v_mfma_f32_16x16x32_bf16 v[20:23], v[216:219], v[200:203], v[20:23]
	v_mfma_f32_16x16x32_bf16 v[16:19], v[236:239], v[200:203], v[16:19]
	v_mfma_f32_16x16x32_bf16 v[4:7], v[216:219], v[208:211], v[4:7]
	v_mfma_f32_16x16x32_bf16 v[0:3], v[236:239], v[208:211], v[0:3]
	s_add_i32 s21, 0, 0x18000
	v_add_u32_e32 v124, s21, v175
	s_barrier
	ds_read_b128 v[112:115], v124
	ds_read_b128 v[116:119], v124 offset:1024
	ds_read_b128 v[120:123], v124 offset:2048
	ds_read_b128 v[124:127], v124 offset:3072
	s_add_u32 s50, s50, 0x100000
	s_addc_u32 s51, s51, 0
	s_mov_b32 m0, s57
	v_lshl_add_u64 v[212:213], s[50:51], 0, v[156:157]
	ds_read_b128 v[132:135], v199 offset:32768
	ds_read_b128 v[136:139], v199 offset:33792
	ds_read_b128 v[162:165], v199 offset:34816
	ds_read_b128 v[166:169], v199 offset:35840
	ds_read_b128 v[170:173], v199 offset:36864
	ds_read_b128 v[200:203], v199 offset:37888
	ds_read_b128 v[204:207], v199 offset:38912
	ds_read_b128 v[208:211], v199 offset:39936
	global_load_lds_dwordx4 v[212:213], off
	v_lshl_add_u64 v[212:213], s[50:51], 0, v[154:155]
	s_mov_b32 m0, s58
	s_nop 0
	global_load_lds_dwordx4 v[212:213], off
	s_waitcnt lgkmcnt(8)
	s_barrier
	s_waitcnt lgkmcnt(0)
	v_mfma_f32_16x16x32_bf16 v[148:151], v[112:115], v[132:135], v[148:151]
	v_mfma_f32_16x16x32_bf16 v[144:147], v[120:123], v[132:135], v[144:147]
	v_mfma_f32_16x16x32_bf16 v[108:111], v[112:115], v[162:165], v[108:111]
	v_mfma_f32_16x16x32_bf16 v[104:107], v[120:123], v[162:165], v[104:107]
	v_mfma_f32_16x16x32_bf16 v[92:95], v[112:115], v[170:173], v[92:95]
	v_mfma_f32_16x16x32_bf16 v[88:91], v[120:123], v[170:173], v[88:91]
	v_mfma_f32_16x16x32_bf16 v[76:79], v[112:115], v[204:207], v[76:79]
	v_mfma_f32_16x16x32_bf16 v[72:75], v[120:123], v[204:207], v[72:75]
	v_mfma_f32_16x16x32_bf16 v[148:151], v[116:119], v[136:139], v[148:151]
	v_mfma_f32_16x16x32_bf16 v[144:147], v[124:127], v[136:139], v[144:147]
	v_mfma_f32_16x16x32_bf16 v[108:111], v[116:119], v[166:169], v[108:111]
	v_mfma_f32_16x16x32_bf16 v[104:107], v[124:127], v[166:169], v[104:107]
	v_mfma_f32_16x16x32_bf16 v[92:95], v[116:119], v[200:203], v[92:95]
	v_mfma_f32_16x16x32_bf16 v[88:91], v[124:127], v[200:203], v[88:91]
	v_mfma_f32_16x16x32_bf16 v[76:79], v[116:119], v[208:211], v[76:79]
	v_mfma_f32_16x16x32_bf16 v[72:75], v[124:127], v[208:211], v[72:75]
	s_barrier
	s_add_i32 s50, 0, 0x1c000
	s_add_i32 s21, s21, s54
	v_add_u32_e32 v231, s50, v175
	v_lshl_add_u64 v[184:185], v[184:185], 0, s[52:53]
	s_mov_b32 m0, s21
	ds_read_b128 v[212:215], v231
	ds_read_b128 v[216:219], v231 offset:1024
	ds_read_b128 v[232:235], v231 offset:2048
	ds_read_b128 v[236:239], v231 offset:3072
	global_load_lds_dwordx4 v[184:185], off
	v_lshl_add_u64 v[184:185], v[192:193], 0, s[52:53]
	s_add_i32 m0, s21, 0x2000
	s_nop 0
	global_load_lds_dwordx4 v[184:185], off
	s_barrier
	s_waitcnt lgkmcnt(0)
	v_mfma_f32_16x16x32_bf16 v[140:143], v[212:215], v[132:135], v[140:143]
	v_mfma_f32_16x16x32_bf16 v[128:131], v[232:235], v[132:135], v[128:131]
	v_mfma_f32_16x16x32_bf16 v[100:103], v[212:215], v[162:165], v[100:103]
	v_mfma_f32_16x16x32_bf16 v[96:99], v[232:235], v[162:165], v[96:99]
	v_mfma_f32_16x16x32_bf16 v[84:87], v[212:215], v[170:173], v[84:87]
	v_mfma_f32_16x16x32_bf16 v[80:83], v[232:235], v[170:173], v[80:83]
	v_mfma_f32_16x16x32_bf16 v[68:71], v[212:215], v[204:207], v[68:71]
	v_mfma_f32_16x16x32_bf16 v[64:67], v[232:235], v[204:207], v[64:67]
	v_mfma_f32_16x16x32_bf16 v[140:143], v[216:219], v[136:139], v[140:143]
	v_mfma_f32_16x16x32_bf16 v[136:139], v[236:239], v[136:139], v[128:131]
	v_mfma_f32_16x16x32_bf16 v[100:103], v[216:219], v[166:169], v[100:103]
	v_mfma_f32_16x16x32_bf16 v[96:99], v[236:239], v[166:169], v[96:99]
	v_mfma_f32_16x16x32_bf16 v[84:87], v[216:219], v[200:203], v[84:87]
	v_mfma_f32_16x16x32_bf16 v[80:83], v[236:239], v[200:203], v[80:83]
	v_mfma_f32_16x16x32_bf16 v[68:71], v[216:219], v[208:211], v[68:71]
	v_mfma_f32_16x16x32_bf16 v[64:67], v[236:239], v[208:211], v[64:67]
	s_mov_b32 m0, s7
	v_lshl_add_u64 v[184:185], v[194:195], 0, s[52:53]
	s_barrier
	ds_read_b128 v[128:131], v199 offset:49152
	ds_read_b128 v[132:135], v199 offset:50176
	ds_read_b128 v[162:165], v199 offset:51200
	ds_read_b128 v[166:169], v199 offset:52224
	ds_read_b128 v[170:173], v199 offset:53248
	ds_read_b128 v[200:203], v199 offset:54272
	ds_read_b128 v[204:207], v199 offset:55296
	ds_read_b128 v[208:211], v199 offset:56320
	global_load_lds_dwordx4 v[184:185], off
	v_lshl_add_u64 v[184:185], v[240:241], 0, s[52:53]
	s_mov_b32 m0, s15
	s_nop 0
	global_load_lds_dwordx4 v[184:185], off
	s_barrier
	s_waitcnt lgkmcnt(0)
	v_mfma_f32_16x16x32_bf16 v[60:63], v[112:115], v[128:131], v[60:63]
	v_mfma_f32_16x16x32_bf16 v[56:59], v[120:123], v[128:131], v[56:59]
	v_mfma_f32_16x16x32_bf16 v[44:47], v[112:115], v[162:165], v[44:47]
	v_mfma_f32_16x16x32_bf16 v[40:43], v[120:123], v[162:165], v[40:43]
	v_mfma_f32_16x16x32_bf16 v[28:31], v[112:115], v[170:173], v[28:31]
	v_mfma_f32_16x16x32_bf16 v[24:27], v[120:123], v[170:173], v[24:27]
	v_mfma_f32_16x16x32_bf16 v[12:15], v[112:115], v[204:207], v[12:15]
	v_mfma_f32_16x16x32_bf16 v[8:11], v[120:123], v[204:207], v[8:11]
	v_mfma_f32_16x16x32_bf16 v[60:63], v[116:119], v[132:135], v[60:63]
	v_mfma_f32_16x16x32_bf16 v[56:59], v[124:127], v[132:135], v[56:59]
	v_mfma_f32_16x16x32_bf16 v[44:47], v[116:119], v[166:169], v[44:47]
	v_mfma_f32_16x16x32_bf16 v[40:43], v[124:127], v[166:169], v[40:43]
	v_mfma_f32_16x16x32_bf16 v[28:31], v[116:119], v[200:203], v[28:31]
	v_mfma_f32_16x16x32_bf16 v[24:27], v[124:127], v[200:203], v[24:27]
	v_mfma_f32_16x16x32_bf16 v[12:15], v[116:119], v[208:211], v[12:15]
	v_mfma_f32_16x16x32_bf16 v[8:11], v[124:127], v[208:211], v[8:11]
	s_barrier
	s_add_u32 s28, s28, 0x100080
	s_addc_u32 s29, s29, 0
	s_add_i32 s21, s50, s54
	v_lshl_add_u64 v[112:113], s[28:29], 0, v[176:177]
	s_mov_b32 m0, s21
	s_nop 0
	global_load_lds_dwordx4 v[112:113], off
	v_lshl_add_u64 v[112:113], s[28:29], 0, v[152:153]
	s_add_i32 m0, s21, 0x2000
	s_nop 0
	global_load_lds_dwordx4 v[112:113], off
	s_waitcnt vmcnt(6)
	s_barrier
	v_mfma_f32_16x16x32_bf16 v[52:55], v[212:215], v[128:131], v[52:55]
	v_mfma_f32_16x16x32_bf16 v[48:51], v[232:235], v[128:131], v[48:51]
	v_mfma_f32_16x16x32_bf16 v[36:39], v[212:215], v[162:165], v[36:39]
	v_mfma_f32_16x16x32_bf16 v[32:35], v[232:235], v[162:165], v[32:35]
	v_mfma_f32_16x16x32_bf16 v[20:23], v[212:215], v[170:173], v[20:23]
	v_mfma_f32_16x16x32_bf16 v[16:19], v[232:235], v[170:173], v[16:19]
	v_mfma_f32_16x16x32_bf16 v[4:7], v[212:215], v[204:207], v[4:7]
	v_mfma_f32_16x16x32_bf16 v[0:3], v[232:235], v[204:207], v[0:3]
	v_mfma_f32_16x16x32_bf16 v[52:55], v[216:219], v[132:135], v[52:55]
	v_mfma_f32_16x16x32_bf16 v[48:51], v[236:239], v[132:135], v[48:51]
	v_mfma_f32_16x16x32_bf16 v[36:39], v[216:219], v[166:169], v[36:39]
	v_mfma_f32_16x16x32_bf16 v[32:35], v[236:239], v[166:169], v[32:35]
	v_mfma_f32_16x16x32_bf16 v[20:23], v[216:219], v[200:203], v[20:23]
	v_mfma_f32_16x16x32_bf16 v[16:19], v[236:239], v[200:203], v[16:19]
	v_mfma_f32_16x16x32_bf16 v[4:7], v[216:219], v[208:211], v[4:7]
	v_mfma_f32_16x16x32_bf16 v[0:3], v[236:239], v[208:211], v[0:3]
	s_add_i32 s20, s20, 2
	s_add_u32 s48, s48, 0x100
	s_addc_u32 s49, s49, 0
	s_add_u32 vcc_lo, vcc_lo, 0x100
	s_addc_u32 vcc_hi, vcc_hi, 0
	s_cmp_gt_u32 s20, 61
	s_barrier
	s_cbranch_scc0 .LBB0_100
	v_lshl_or_b32 v162, s34, 8, v198
	v_lshl_add_u32 v166, s2, 8, v174
	v_ashrrev_i32_e32 v163, 31, v162
	v_lshlrev_b64 v[184:185], 1, v[162:163]
	v_ashrrev_i32_e32 v167, 31, v166
	v_lshl_add_u64 v[164:165], s[68:69], 0, v[184:185]
	v_lshlrev_b64 v[192:193], 11, v[166:167]
	v_lshl_add_u64 v[112:113], v[164:165], 0, v[192:193]
	global_load_dwordx4 v[200:203], v[112:113], off
	global_load_dwordx4 v[204:207], v[112:113], off offset:256
	v_or_b32_e32 v172, 16, v166
	v_ashrrev_i32_e32 v173, 31, v172
	v_lshlrev_b64 v[112:113], 11, v[172:173]
	v_or_b32_e32 v170, 32, v166
	v_lshl_add_u64 v[112:113], v[164:165], 0, v[112:113]
	v_ashrrev_i32_e32 v171, 31, v170
	global_load_dwordx4 v[132:135], v[112:113], off
	global_load_dwordx4 v[128:131], v[112:113], off offset:256
	v_lshlrev_b64 v[112:113], 11, v[170:171]
	v_or_b32_e32 v168, 48, v166
	v_lshl_add_u64 v[112:113], v[164:165], 0, v[112:113]
	v_ashrrev_i32_e32 v169, 31, v168
	global_load_dwordx4 v[124:127], v[112:113], off
	global_load_dwordx4 v[120:123], v[112:113], off offset:256
	v_lshlrev_b64 v[112:113], 11, v[168:169]
	v_lshl_add_u64 v[112:113], v[164:165], 0, v[112:113]
	global_load_dwordx4 v[116:119], v[112:113], off
	s_nop 0
	global_load_dwordx4 v[112:115], v[112:113], off offset:256
	v_add_u32_e32 v214, 0x80, v166
	v_ashrrev_i32_e32 v215, 31, v214
	v_lshlrev_b64 v[214:215], 11, v[214:215]
	v_lshl_add_u64 v[214:215], v[164:165], 0, v[214:215]
	global_load_dwordx4 v[208:211], v[214:215], off
	s_nop 0
	global_load_dwordx4 v[212:215], v[214:215], off offset:256
	v_add_u32_e32 v234, 0x90, v166
	v_ashrrev_i32_e32 v235, 31, v234
	v_lshlrev_b64 v[234:235], 11, v[234:235]
	v_lshl_add_u64 v[234:235], v[164:165], 0, v[234:235]
	global_load_dwordx4 v[216:219], v[234:235], off
	s_nop 0
	global_load_dwordx4 v[232:235], v[234:235], off offset:256
	v_add_u32_e32 v242, 0xa0, v166
	v_ashrrev_i32_e32 v243, 31, v242
	v_lshlrev_b64 v[242:243], 11, v[242:243]
	v_lshl_add_u64 v[242:243], v[164:165], 0, v[242:243]
	global_load_dwordx4 v[236:239], v[242:243], off
	s_nop 0
	global_load_dwordx4 v[240:243], v[242:243], off offset:256
	v_add_u32_e32 v250, 0xb0, v166
	v_ashrrev_i32_e32 v251, 31, v250
	v_lshlrev_b64 v[250:251], 11, v[250:251]
	v_lshl_add_u64 v[250:251], v[164:165], 0, v[250:251]
	global_load_dwordx4 v[244:247], v[250:251], off
	s_nop 0
	global_load_dwordx4 v[248:251], v[250:251], off offset:256
	s_lshl_b32 s48, s34, 2
	s_ashr_i32 s49, s48, 31
	s_waitcnt vmcnt(8)
	v_lshlrev_b32_e32 v194, 16, v200
	v_add_f32_e32 v148, v148, v194
	v_and_b32_e32 v194, 0xffff0000, v200
	v_add_f32_e32 v149, v149, v194
	v_lshlrev_b32_e32 v194, 16, v201
	v_add_f32_e32 v150, v150, v194
	v_and_b32_e32 v194, 0xffff0000, v201
	v_add_f32_e32 v151, v151, v194
	v_lshlrev_b32_e32 v194, 16, v202
	v_add_f32_e32 v194, v144, v194
	v_and_b32_e32 v144, 0xffff0000, v202
	v_add_f32_e32 v195, v145, v144
	v_lshlrev_b32_e32 v144, 16, v203
	v_add_f32_e32 v200, v146, v144
	v_and_b32_e32 v144, 0xffff0000, v203
	v_add_f32_e32 v147, v147, v144
	v_mul_f32_e32 v144, v194, v194
	v_mul_f32_e32 v145, v195, v195
	v_fmac_f32_e32 v144, v148, v148
	v_fmac_f32_e32 v145, v149, v149
	v_add_f32_e32 v144, v144, v145
	v_mul_f32_e32 v145, v200, v200
	v_fmac_f32_e32 v145, v150, v150
	v_add_f32_e32 v144, v145, v144
	v_mul_f32_e32 v145, v147, v147
	v_fmac_f32_e32 v145, v151, v151
	v_add_f32_e32 v201, v145, v144
	v_cvt_pk_bf16_f32 v144, v148, v149
	v_lshl_add_u64 v[148:149], s[64:65], 0, v[192:193]
	v_lshl_add_u64 v[148:149], v[148:149], 0, v[184:185]
	v_cvt_pk_bf16_f32 v145, v150, v151
	v_cvt_pk_bf16_f32 v146, v194, v195
	v_cvt_pk_bf16_f32 v147, v200, v147
	global_store_dwordx4 v[148:149], v[144:147], off
	s_nop 1
	v_lshlrev_b32_e32 v144, 16, v204
	v_add_f32_e32 v140, v140, v144
	v_and_b32_e32 v144, 0xffff0000, v204
	v_add_f32_e32 v141, v141, v144
	v_lshlrev_b32_e32 v144, 16, v205
	v_add_f32_e32 v142, v142, v144
	v_and_b32_e32 v144, 0xffff0000, v205
	v_add_f32_e32 v143, v143, v144
	v_lshlrev_b32_e32 v144, 16, v206
	v_add_f32_e32 v144, v136, v144
	v_and_b32_e32 v136, 0xffff0000, v206
	v_add_f32_e32 v145, v137, v136
	v_lshlrev_b32_e32 v136, 16, v207
	v_add_f32_e32 v146, v138, v136
	v_and_b32_e32 v136, 0xffff0000, v207
	v_add_f32_e32 v139, v139, v136
	v_mul_f32_e32 v136, v144, v144
	v_fmac_f32_e32 v136, v140, v140
	v_mul_f32_e32 v137, v145, v145
	v_add_f32_e32 v136, v136, v201
	v_fmac_f32_e32 v137, v141, v141
	v_add_f32_e32 v136, v137, v136
	v_mul_f32_e32 v137, v146, v146
	v_fmac_f32_e32 v137, v142, v142
	v_add_f32_e32 v136, v137, v136
	v_mul_f32_e32 v137, v139, v139
	v_fmac_f32_e32 v137, v143, v143
	v_add_f32_e32 v147, v137, v136
	v_cvt_pk_bf16_f32 v136, v140, v141
	v_cvt_pk_bf16_f32 v137, v142, v143
	v_cvt_pk_bf16_f32 v138, v144, v145
	v_cvt_pk_bf16_f32 v139, v146, v139
	global_store_dwordx4 v[148:149], v[136:139], off offset:256
	s_nop 1
	v_and_b32_e32 v137, 64, v225
	v_xor_b32_e32 v136, 16, v225
	v_add_u32_e32 v137, 64, v137
	v_cmp_lt_i32_e32 vcc, v136, v137
	v_xor_b32_e32 v139, 32, v225
	s_nop 0
	v_cndmask_b32_e32 v136, v225, v136, vcc
	v_lshlrev_b32_e32 v136, 2, v136
	ds_bpermute_b32 v138, v136, v147
	v_cmp_lt_i32_e32 vcc, v139, v137
	s_waitcnt lgkmcnt(0)
	v_add_f32_e32 v138, v147, v138
	v_cndmask_b32_e32 v137, v225, v139, vcc
	v_lshlrev_b32_e32 v137, 2, v137
	ds_bpermute_b32 v139, v137, v138
	s_and_saveexec_b64 s[28:29], s[38:39]
	s_cbranch_execz .LBB0_103
	v_lshlrev_b64 v[140:141], 6, v[166:167]
	v_lshl_add_u64 v[140:141], s[62:63], 0, v[140:141]
	v_lshl_add_u64 v[140:141], s[48:49], 2, v[140:141]
	s_lshl_b32 s34, s9, 2
	v_lshl_add_u64 v[140:141], v[140:141], 0, s[34:35]
	s_waitcnt lgkmcnt(0)
	v_add_f32_e32 v138, v138, v139
	global_store_dword v[140:141], v138, off

.LBB0_147:
	s_add_u32 s21, s0, 0xfffc0080
	s_addc_u32 s28, s1, -1
	s_add_i32 s60, 0, 0x10000
	v_add_u32_e32 v140, s60, v205
	ds_read_b128 v[128:131], v140
	ds_read_b128 v[132:135], v140 offset:1024
	ds_read_b128 v[136:139], v140 offset:2048
	ds_read_b128 v[140:143], v140 offset:3072
	s_cmp_eq_u32 s20, 12
	s_cselect_b32 s49, s43, s28
	s_cselect_b32 s48, s24, s21
	s_cselect_b32 s29, s25, vcc_hi
	s_cselect_b32 s28, s41, vcc_lo
	v_lshl_add_u64 v[174:175], s[0:1], 0, v[150:151]
	s_add_i32 m0, s57, 0xc000
	ds_read_b128 v[154:157], v208
	ds_read_b128 v[158:161], v208 offset:1024
	ds_read_b128 v[162:165], v208 offset:2048
	ds_read_b128 v[166:169], v208 offset:3072
	ds_read_b128 v[170:173], v208 offset:4096
	ds_read_b128 v[198:201], v208 offset:5120
	ds_read_b128 v[210:213], v208 offset:6144
	ds_read_b128 v[214:217], v208 offset:7168
	global_load_lds_dwordx4 v[174:175], off
	v_lshl_add_u64 v[174:175], s[0:1], 0, v[152:153]
	s_add_i32 m0, s57, 0xe000
	s_nop 0
	global_load_lds_dwordx4 v[174:175], off
	s_waitcnt lgkmcnt(8)
	s_barrier
	s_waitcnt lgkmcnt(0)
	v_mfma_f32_16x16x32_bf16 v[124:127], v[128:131], v[154:157], v[124:127]
	v_mfma_f32_16x16x32_bf16 v[120:123], v[136:139], v[154:157], v[120:123]
	v_mfma_f32_16x16x32_bf16 v[108:111], v[128:131], v[162:165], v[108:111]
	v_mfma_f32_16x16x32_bf16 v[104:107], v[136:139], v[162:165], v[104:107]
	v_mfma_f32_16x16x32_bf16 v[92:95], v[128:131], v[170:173], v[92:95]
	v_mfma_f32_16x16x32_bf16 v[88:91], v[136:139], v[170:173], v[88:91]
	v_mfma_f32_16x16x32_bf16 v[76:79], v[128:131], v[210:213], v[76:79]
	v_mfma_f32_16x16x32_bf16 v[72:75], v[136:139], v[210:213], v[72:75]
	v_mfma_f32_16x16x32_bf16 v[124:127], v[132:135], v[158:161], v[124:127]
	v_mfma_f32_16x16x32_bf16 v[120:123], v[140:143], v[158:161], v[120:123]
	v_mfma_f32_16x16x32_bf16 v[108:111], v[132:135], v[166:169], v[108:111]
	v_mfma_f32_16x16x32_bf16 v[104:107], v[140:143], v[166:169], v[104:107]
	v_mfma_f32_16x16x32_bf16 v[92:95], v[132:135], v[198:201], v[92:95]
	v_mfma_f32_16x16x32_bf16 v[88:91], v[140:143], v[198:201], v[88:91]
	v_mfma_f32_16x16x32_bf16 v[76:79], v[132:135], v[214:217], v[76:79]
	v_mfma_f32_16x16x32_bf16 v[72:75], v[140:143], v[214:217], v[72:75]
	s_barrier
	s_add_i32 s21, 0, 0x14000
	v_add_u32_e32 v174, s21, v205
	s_add_i32 s60, s60, s56
	ds_read_b128 v[232:235], v174
	ds_read_b128 v[236:239], v174 offset:1024
	ds_read_b128 v[240:243], v174 offset:2048
	ds_read_b128 v[244:247], v174 offset:3072
	v_lshl_add_u64 v[174:175], s[28:29], 0, v[176:177]
	s_mov_b32 m0, s60
	v_lshl_add_u64 v[184:185], s[28:29], 0, v[144:145]
	global_load_lds_dwordx4 v[174:175], off
	s_add_i32 m0, s60, 0x2000
	s_nop 0
	global_load_lds_dwordx4 v[184:185], off
	s_barrier
	s_waitcnt lgkmcnt(0)
	v_mfma_f32_16x16x32_bf16 v[116:119], v[232:235], v[154:157], v[116:119]
	v_mfma_f32_16x16x32_bf16 v[112:115], v[240:243], v[154:157], v[112:115]
	v_mfma_f32_16x16x32_bf16 v[100:103], v[232:235], v[162:165], v[100:103]
	v_mfma_f32_16x16x32_bf16 v[96:99], v[240:243], v[162:165], v[96:99]
	v_mfma_f32_16x16x32_bf16 v[84:87], v[232:235], v[170:173], v[84:87]
	v_mfma_f32_16x16x32_bf16 v[80:83], v[240:243], v[170:173], v[80:83]
	v_mfma_f32_16x16x32_bf16 v[68:71], v[232:235], v[210:213], v[68:71]
	v_mfma_f32_16x16x32_bf16 v[64:67], v[240:243], v[210:213], v[64:67]
	v_mfma_f32_16x16x32_bf16 v[116:119], v[236:239], v[158:161], v[116:119]
	v_mfma_f32_16x16x32_bf16 v[112:115], v[244:247], v[158:161], v[112:115]
	v_mfma_f32_16x16x32_bf16 v[100:103], v[236:239], v[166:169], v[100:103]
	v_mfma_f32_16x16x32_bf16 v[96:99], v[244:247], v[166:169], v[96:99]
	v_mfma_f32_16x16x32_bf16 v[84:87], v[236:239], v[198:201], v[84:87]
	v_mfma_f32_16x16x32_bf16 v[80:83], v[244:247], v[198:201], v[80:83]
	v_mfma_f32_16x16x32_bf16 v[68:71], v[236:239], v[214:217], v[68:71]
	v_mfma_f32_16x16x32_bf16 v[64:67], v[244:247], v[214:217], v[64:67]
	s_mov_b32 m0, s57
	v_lshl_add_u64 v[192:193], s[48:49], 0, v[148:149]
	s_barrier
	ds_read_b128 v[154:157], v208 offset:16384
	ds_read_b128 v[158:161], v208 offset:17408
	ds_read_b128 v[162:165], v208 offset:18432
	ds_read_b128 v[166:169], v208 offset:19456
	ds_read_b128 v[170:173], v208 offset:20480
	ds_read_b128 v[198:201], v208 offset:21504
	ds_read_b128 v[210:213], v208 offset:22528
	ds_read_b128 v[214:217], v208 offset:23552
	global_load_lds_dwordx4 v[192:193], off
	v_lshl_add_u64 v[194:195], s[48:49], 0, v[146:147]
	s_mov_b32 m0, s58
	s_nop 0
	global_load_lds_dwordx4 v[194:195], off
	s_barrier
	s_waitcnt lgkmcnt(0)
	v_mfma_f32_16x16x32_bf16 v[60:63], v[128:131], v[154:157], v[60:63]
	v_mfma_f32_16x16x32_bf16 v[56:59], v[136:139], v[154:157], v[56:59]
	v_mfma_f32_16x16x32_bf16 v[44:47], v[128:131], v[162:165], v[44:47]
	v_mfma_f32_16x16x32_bf16 v[40:43], v[136:139], v[162:165], v[40:43]
	v_mfma_f32_16x16x32_bf16 v[28:31], v[128:131], v[170:173], v[28:31]
	v_mfma_f32_16x16x32_bf16 v[24:27], v[136:139], v[170:173], v[24:27]
	v_mfma_f32_16x16x32_bf16 v[12:15], v[128:131], v[210:213], v[12:15]
	v_mfma_f32_16x16x32_bf16 v[8:11], v[136:139], v[210:213], v[8:11]
	v_mfma_f32_16x16x32_bf16 v[60:63], v[132:135], v[158:161], v[60:63]
	v_mfma_f32_16x16x32_bf16 v[56:59], v[140:143], v[158:161], v[56:59]
	v_mfma_f32_16x16x32_bf16 v[44:47], v[132:135], v[166:169], v[44:47]
	v_mfma_f32_16x16x32_bf16 v[40:43], v[140:143], v[166:169], v[40:43]
	v_mfma_f32_16x16x32_bf16 v[28:31], v[132:135], v[198:201], v[28:31]
	v_mfma_f32_16x16x32_bf16 v[24:27], v[140:143], v[198:201], v[24:27]
	v_mfma_f32_16x16x32_bf16 v[12:15], v[132:135], v[214:217], v[12:15]
	v_mfma_f32_16x16x32_bf16 v[8:11], v[140:143], v[214:217], v[8:11]
	s_barrier
	s_add_u32 s60, s28, 0x40000
	s_addc_u32 s61, s29, 0
	s_add_i32 s21, s21, s56
	v_lshl_add_u64 v[128:129], s[60:61], 0, v[176:177]
	s_mov_b32 m0, s21
	s_nop 0
	global_load_lds_dwordx4 v[128:129], off
	v_lshl_add_u64 v[128:129], s[60:61], 0, v[144:145]
	s_add_i32 m0, s21, 0x2000
	s_nop 0
	global_load_lds_dwordx4 v[128:129], off
	s_waitcnt vmcnt(6)
	s_barrier
	v_mfma_f32_16x16x32_bf16 v[52:55], v[232:235], v[154:157], v[52:55]
	v_mfma_f32_16x16x32_bf16 v[48:51], v[240:243], v[154:157], v[48:51]
	v_mfma_f32_16x16x32_bf16 v[36:39], v[232:235], v[162:165], v[36:39]
	v_mfma_f32_16x16x32_bf16 v[32:35], v[240:243], v[162:165], v[32:35]
	v_mfma_f32_16x16x32_bf16 v[20:23], v[232:235], v[170:173], v[20:23]
	v_mfma_f32_16x16x32_bf16 v[16:19], v[240:243], v[170:173], v[16:19]
	v_mfma_f32_16x16x32_bf16 v[4:7], v[232:235], v[210:213], v[4:7]
	v_mfma_f32_16x16x32_bf16 v[0:3], v[240:243], v[210:213], v[0:3]
	v_mfma_f32_16x16x32_bf16 v[52:55], v[236:239], v[158:161], v[52:55]
	v_mfma_f32_16x16x32_bf16 v[48:51], v[244:247], v[158:161], v[48:51]
	v_mfma_f32_16x16x32_bf16 v[36:39], v[236:239], v[166:169], v[36:39]
	v_mfma_f32_16x16x32_bf16 v[32:35], v[244:247], v[166:169], v[32:35]
	v_mfma_f32_16x16x32_bf16 v[20:23], v[236:239], v[198:201], v[20:23]
	v_mfma_f32_16x16x32_bf16 v[16:19], v[244:247], v[198:201], v[16:19]
	v_mfma_f32_16x16x32_bf16 v[4:7], v[236:239], v[214:217], v[4:7]
	v_mfma_f32_16x16x32_bf16 v[0:3], v[244:247], v[214:217], v[0:3]
	s_add_i32 s21, 0, 0x18000
	v_add_u32_e32 v140, s21, v205
	s_barrier
	ds_read_b128 v[128:131], v140
	ds_read_b128 v[132:135], v140 offset:1024
	ds_read_b128 v[136:139], v140 offset:2048
	ds_read_b128 v[140:143], v140 offset:3072
	s_add_u32 s48, s48, 0x40000
	s_addc_u32 s49, s49, 0
	s_mov_b32 m0, s7
	v_lshl_add_u64 v[202:203], s[48:49], 0, v[148:149]
	ds_read_b128 v[154:157], v208 offset:32768
	ds_read_b128 v[158:161], v208 offset:33792
	ds_read_b128 v[162:165], v208 offset:34816
	ds_read_b128 v[166:169], v208 offset:35840
	ds_read_b128 v[170:173], v208 offset:36864
	ds_read_b128 v[198:201], v208 offset:37888
	ds_read_b128 v[210:213], v208 offset:38912
	ds_read_b128 v[214:217], v208 offset:39936
	global_load_lds_dwordx4 v[202:203], off
	v_lshl_add_u64 v[202:203], s[48:49], 0, v[146:147]
	s_mov_b32 m0, s15
	s_nop 0
	global_load_lds_dwordx4 v[202:203], off
	s_waitcnt lgkmcnt(8)
	s_barrier
	s_waitcnt lgkmcnt(0)
	v_mfma_f32_16x16x32_bf16 v[124:127], v[128:131], v[154:157], v[124:127]
	v_mfma_f32_16x16x32_bf16 v[120:123], v[136:139], v[154:157], v[120:123]
	v_mfma_f32_16x16x32_bf16 v[108:111], v[128:131], v[162:165], v[108:111]
	v_mfma_f32_16x16x32_bf16 v[104:107], v[136:139], v[162:165], v[104:107]
	v_mfma_f32_16x16x32_bf16 v[92:95], v[128:131], v[170:173], v[92:95]
	v_mfma_f32_16x16x32_bf16 v[88:91], v[136:139], v[170:173], v[88:91]
	v_mfma_f32_16x16x32_bf16 v[76:79], v[128:131], v[210:213], v[76:79]
	v_mfma_f32_16x16x32_bf16 v[72:75], v[136:139], v[210:213], v[72:75]
	v_mfma_f32_16x16x32_bf16 v[124:127], v[132:135], v[158:161], v[124:127]
	v_mfma_f32_16x16x32_bf16 v[120:123], v[140:143], v[158:161], v[120:123]
	v_mfma_f32_16x16x32_bf16 v[108:111], v[132:135], v[166:169], v[108:111]
	v_mfma_f32_16x16x32_bf16 v[104:107], v[140:143], v[166:169], v[104:107]
	v_mfma_f32_16x16x32_bf16 v[92:95], v[132:135], v[198:201], v[92:95]
	v_mfma_f32_16x16x32_bf16 v[88:91], v[140:143], v[198:201], v[88:91]
	v_mfma_f32_16x16x32_bf16 v[76:79], v[132:135], v[214:217], v[76:79]
	v_mfma_f32_16x16x32_bf16 v[72:75], v[140:143], v[214:217], v[72:75]
	s_barrier
	s_add_i32 s48, 0, 0x1c000
	s_add_i32 s21, s21, s56
	v_add_u32_e32 v202, s48, v205
	v_lshl_add_u64 v[174:175], v[174:175], 0, s[52:53]
	s_mov_b32 m0, s21
	ds_read_b128 v[232:235], v202
	ds_read_b128 v[236:239], v202 offset:1024
	ds_read_b128 v[240:243], v202 offset:2048
	ds_read_b128 v[244:247], v202 offset:3072
	global_load_lds_dwordx4 v[174:175], off
	v_lshl_add_u64 v[174:175], v[184:185], 0, s[52:53]
	s_add_i32 m0, s21, 0x2000
	s_nop 0
	global_load_lds_dwordx4 v[174:175], off
	s_barrier
	s_waitcnt lgkmcnt(0)
	v_mfma_f32_16x16x32_bf16 v[116:119], v[232:235], v[154:157], v[116:119]
	v_mfma_f32_16x16x32_bf16 v[112:115], v[240:243], v[154:157], v[112:115]
	v_mfma_f32_16x16x32_bf16 v[100:103], v[232:235], v[162:165], v[100:103]
	v_mfma_f32_16x16x32_bf16 v[96:99], v[240:243], v[162:165], v[96:99]
	v_mfma_f32_16x16x32_bf16 v[84:87], v[232:235], v[170:173], v[84:87]
	v_mfma_f32_16x16x32_bf16 v[80:83], v[240:243], v[170:173], v[80:83]
	v_mfma_f32_16x16x32_bf16 v[68:71], v[232:235], v[210:213], v[68:71]
	v_mfma_f32_16x16x32_bf16 v[64:67], v[240:243], v[210:213], v[64:67]
	v_mfma_f32_16x16x32_bf16 v[116:119], v[236:239], v[158:161], v[116:119]
	v_mfma_f32_16x16x32_bf16 v[112:115], v[244:247], v[158:161], v[112:115]
	v_mfma_f32_16x16x32_bf16 v[100:103], v[236:239], v[166:169], v[100:103]
	v_mfma_f32_16x16x32_bf16 v[96:99], v[244:247], v[166:169], v[96:99]
	v_mfma_f32_16x16x32_bf16 v[84:87], v[236:239], v[198:201], v[84:87]
	v_mfma_f32_16x16x32_bf16 v[80:83], v[244:247], v[198:201], v[80:83]
	v_mfma_f32_16x16x32_bf16 v[68:71], v[236:239], v[214:217], v[68:71]
	v_mfma_f32_16x16x32_bf16 v[64:67], v[244:247], v[214:217], v[64:67]
	s_mov_b32 m0, s3
	v_lshl_add_u64 v[174:175], v[192:193], 0, s[52:53]
	s_barrier
	ds_read_b128 v[154:157], v208 offset:49152
	ds_read_b128 v[158:161], v208 offset:50176
	ds_read_b128 v[162:165], v208 offset:51200
	ds_read_b128 v[166:169], v208 offset:52224
	ds_read_b128 v[170:173], v208 offset:53248
	ds_read_b128 v[198:201], v208 offset:54272
	ds_read_b128 v[210:213], v208 offset:55296
	ds_read_b128 v[214:217], v208 offset:56320
	global_load_lds_dwordx4 v[174:175], off
	v_lshl_add_u64 v[174:175], v[194:195], 0, s[52:53]
	s_mov_b32 m0, s6
	s_nop 0
	global_load_lds_dwordx4 v[174:175], off
	s_barrier
	s_waitcnt lgkmcnt(0)
	v_mfma_f32_16x16x32_bf16 v[60:63], v[128:131], v[154:157], v[60:63]
	v_mfma_f32_16x16x32_bf16 v[56:59], v[136:139], v[154:157], v[56:59]
	v_mfma_f32_16x16x32_bf16 v[44:47], v[128:131], v[162:165], v[44:47]
	v_mfma_f32_16x16x32_bf16 v[40:43], v[136:139], v[162:165], v[40:43]
	v_mfma_f32_16x16x32_bf16 v[28:31], v[128:131], v[170:173], v[28:31]
	v_mfma_f32_16x16x32_bf16 v[24:27], v[136:139], v[170:173], v[24:27]
	v_mfma_f32_16x16x32_bf16 v[12:15], v[128:131], v[210:213], v[12:15]
	v_mfma_f32_16x16x32_bf16 v[8:11], v[136:139], v[210:213], v[8:11]
	v_mfma_f32_16x16x32_bf16 v[60:63], v[132:135], v[158:161], v[60:63]
	v_mfma_f32_16x16x32_bf16 v[56:59], v[140:143], v[158:161], v[56:59]
	v_mfma_f32_16x16x32_bf16 v[44:47], v[132:135], v[166:169], v[44:47]
	v_mfma_f32_16x16x32_bf16 v[40:43], v[140:143], v[166:169], v[40:43]
	v_mfma_f32_16x16x32_bf16 v[28:31], v[132:135], v[198:201], v[28:31]
	v_mfma_f32_16x16x32_bf16 v[24:27], v[140:143], v[198:201], v[24:27]
	v_mfma_f32_16x16x32_bf16 v[12:15], v[132:135], v[214:217], v[12:15]
	v_mfma_f32_16x16x32_bf16 v[8:11], v[140:143], v[214:217], v[8:11]
	s_barrier
	s_add_u32 s28, s28, 0x40080
	s_addc_u32 s29, s29, 0
	s_add_i32 s21, s48, s56
	v_lshl_add_u64 v[128:129], s[28:29], 0, v[176:177]
	s_mov_b32 m0, s21
	s_nop 0
	global_load_lds_dwordx4 v[128:129], off
	v_lshl_add_u64 v[128:129], s[28:29], 0, v[144:145]
	s_add_i32 m0, s21, 0x2000
	s_nop 0
	global_load_lds_dwordx4 v[128:129], off
	s_waitcnt vmcnt(6)
	s_barrier
	v_mfma_f32_16x16x32_bf16 v[52:55], v[232:235], v[154:157], v[52:55]
	v_mfma_f32_16x16x32_bf16 v[48:51], v[240:243], v[154:157], v[48:51]
	v_mfma_f32_16x16x32_bf16 v[36:39], v[232:235], v[162:165], v[36:39]
	v_mfma_f32_16x16x32_bf16 v[32:35], v[240:243], v[162:165], v[32:35]
	v_mfma_f32_16x16x32_bf16 v[20:23], v[232:235], v[170:173], v[20:23]
	v_mfma_f32_16x16x32_bf16 v[16:19], v[240:243], v[170:173], v[16:19]
	v_mfma_f32_16x16x32_bf16 v[4:7], v[232:235], v[210:213], v[4:7]
	v_mfma_f32_16x16x32_bf16 v[0:3], v[240:243], v[210:213], v[0:3]
	v_mfma_f32_16x16x32_bf16 v[52:55], v[236:239], v[158:161], v[52:55]
	v_mfma_f32_16x16x32_bf16 v[48:51], v[244:247], v[158:161], v[48:51]
	v_mfma_f32_16x16x32_bf16 v[36:39], v[236:239], v[166:169], v[36:39]
	v_mfma_f32_16x16x32_bf16 v[32:35], v[244:247], v[166:169], v[32:35]
	v_mfma_f32_16x16x32_bf16 v[20:23], v[236:239], v[198:201], v[20:23]
	v_mfma_f32_16x16x32_bf16 v[16:19], v[244:247], v[198:201], v[16:19]
	v_mfma_f32_16x16x32_bf16 v[4:7], v[236:239], v[214:217], v[4:7]
	v_mfma_f32_16x16x32_bf16 v[0:3], v[244:247], v[214:217], v[0:3]
	s_add_i32 s20, s20, 2
	s_add_u32 s0, s0, 0x100
	s_addc_u32 s1, s1, 0
	s_add_u32 vcc_lo, vcc_lo, 0x100
	s_addc_u32 vcc_hi, vcc_hi, 0
	s_cmp_gt_u32 s20, 13
	s_barrier
	s_cbranch_scc0 .LBB0_147
	s_cmp_eq_u32 s2, s51
	s_cselect_b64 s[48:49], -1, 0
	s_cmp_eq_u32 s2, s50
	v_lshl_add_u32 v170, s2, 8, v204
	s_cselect_b64 s[0:1], -1, 0
	s_or_b64 s[20:21], s[48:49], s[0:1]
	v_or_b32_e32 v166, 16, v170
	v_or_b32_e32 v164, 32, v170
	v_or_b32_e32 v162, 48, v170
	v_add_u32_e32 v160, 0x80, v170
	v_add_u32_e32 v158, 0x90, v170
	v_add_u32_e32 v156, 0xa0, v170
	v_add_u32_e32 v154, 0xb0, v170
	s_mov_b64 s[0:1], -1
	s_and_b64 vcc, exec, s[20:21]
	v_ashrrev_i32_e32 v171, 31, v170
	v_ashrrev_i32_e32 v167, 31, v166
	v_ashrrev_i32_e32 v165, 31, v164
	v_ashrrev_i32_e32 v163, 31, v162
	v_ashrrev_i32_e32 v161, 31, v160
	v_ashrrev_i32_e32 v159, 31, v158
	v_ashrrev_i32_e32 v157, 31, v156
	v_ashrrev_i32_e32 v155, 31, v154
	s_cbranch_vccnz .LBB0_150
	v_readlane_b32 s20, v253, 31
	v_lshlrev_b64 v[128:129], 6, v[170:171]
	v_readlane_b32 s21, v253, 32
	s_mov_b32 s0, 0x3727c5ac
	v_mov_b64_e32 v[198:199], s[0:1]
	v_lshl_add_u64 v[140:141], s[20:21], 0, v[128:129]
	global_load_dwordx4 v[128:131], v[140:141], off offset:32
	global_load_dwordx4 v[132:135], v[140:141], off offset:48
	global_load_dwordx4 v[136:139], v[140:141], off
	s_nop 0
	global_load_dwordx4 v[140:143], v[140:141], off offset:16
	s_mov_b32 s2, 0x3a800000
	s_mov_b32 s24, 0x45800000
	s_waitcnt vmcnt(0)
	v_pk_add_f32 v[128:129], v[128:129], v[132:133]
	v_pk_add_f32 v[130:131], v[130:131], v[134:135]
	v_pk_add_f32 v[136:137], v[136:137], v[140:141]
	v_pk_add_f32 v[138:139], v[138:139], v[142:143]
	v_pk_add_f32 v[172:173], v[136:137], v[128:129]
	v_lshlrev_b64 v[128:129], 6, v[166:167]
	v_lshl_add_u64 v[140:141], s[20:21], 0, v[128:129]
	v_pk_add_f32 v[168:169], v[138:139], v[130:131]
	global_load_dwordx4 v[128:131], v[140:141], off offset:32
	global_load_dwordx4 v[132:135], v[140:141], off offset:48
	global_load_dwordx4 v[136:139], v[140:141], off
	s_nop 0
	global_load_dwordx4 v[140:143], v[140:141], off offset:16
	s_waitcnt vmcnt(0)
	v_pk_add_f32 v[128:129], v[128:129], v[132:133]
	v_pk_add_f32 v[130:131], v[130:131], v[134:135]
	v_pk_add_f32 v[136:137], v[136:137], v[140:141]
	v_pk_add_f32 v[138:139], v[138:139], v[142:143]
	v_pk_add_f32 v[128:129], v[136:137], v[128:129]
	v_pk_add_f32 v[130:131], v[138:139], v[130:131]
	v_mov_b32_e32 v132, v128
	v_mov_b32_e32 v133, v172
	v_mov_b32_e32 v172, v129
	v_pk_add_f32 v[128:129], v[132:133], v[172:173]
	v_mov_b32_e32 v132, v130
	v_mov_b32_e32 v133, v168
	v_pk_add_f32 v[128:129], v[132:133], v[128:129]
	v_mov_b32_e32 v168, v131
	v_pk_add_f32 v[128:129], v[168:169], v[128:129]
	s_nop 0
	v_pk_fma_f32 v[128:129], v[128:129], s[2:3], v[198:199] op_sel_hi:[1,0,0]
	s_nop 0
	v_mul_f32_e32 v130, 0x4b800000, v129
	v_cmp_gt_f32_e64 s[0:1], s23, v129
	v_cmp_gt_f32_e32 vcc, s23, v128
	s_nop 0
	v_cndmask_b32_e64 v129, v129, v130, s[0:1]
	v_mul_f32_e32 v130, 0x4b800000, v128
	v_cndmask_b32_e32 v128, v128, v130, vcc
	v_rsq_f32_e32 v129, v129
	v_rsq_f32_e32 v128, v128
	s_nop 0
	v_pk_mul_f32 v[130:131], v[128:129], s[24:25] op_sel_hi:[1,0]
	s_nop 0
	v_cndmask_b32_e32 v169, v128, v130, vcc
	v_cndmask_b32_e64 v168, v129, v131, s[0:1]
	v_lshlrev_b64 v[128:129], 6, v[164:165]
	v_lshl_add_u64 v[140:141], s[20:21], 0, v[128:129]
	global_load_dwordx4 v[128:131], v[140:141], off offset:32
	global_load_dwordx4 v[132:135], v[140:141], off offset:48
	global_load_dwordx4 v[136:139], v[140:141], off
	s_nop 0
	global_load_dwordx4 v[140:143], v[140:141], off offset:16
	s_waitcnt vmcnt(0)
	v_pk_add_f32 v[128:129], v[128:129], v[132:133]
	v_pk_add_f32 v[130:131], v[130:131], v[134:135]
	v_pk_add_f32 v[136:137], v[136:137], v[140:141]
	v_pk_add_f32 v[138:139], v[138:139], v[142:143]
	v_pk_add_f32 v[174:175], v[136:137], v[128:129]
	v_lshlrev_b64 v[128:129], 6, v[162:163]
	v_lshl_add_u64 v[140:141], s[20:21], 0, v[128:129]
	v_pk_add_f32 v[172:173], v[138:139], v[130:131]
	global_load_dwordx4 v[128:131], v[140:141], off offset:32
	global_load_dwordx4 v[132:135], v[140:141], off offset:48
	global_load_dwordx4 v[136:139], v[140:141], off
	s_nop 0
	global_load_dwordx4 v[140:143], v[140:141], off offset:16
	s_waitcnt vmcnt(0)
	v_pk_add_f32 v[128:129], v[128:129], v[132:133]
	v_pk_add_f32 v[130:131], v[130:131], v[134:135]
	v_pk_add_f32 v[136:137], v[136:137], v[140:141]
	v_pk_add_f32 v[138:139], v[138:139], v[142:143]
	v_pk_add_f32 v[128:129], v[136:137], v[128:129]
	v_pk_add_f32 v[130:131], v[138:139], v[130:131]
	v_mov_b32_e32 v132, v128
	v_mov_b32_e32 v133, v174
	v_mov_b32_e32 v174, v129
	v_pk_add_f32 v[128:129], v[132:133], v[174:175]
	v_mov_b32_e32 v132, v130
	v_mov_b32_e32 v133, v172
	v_pk_add_f32 v[128:129], v[132:133], v[128:129]
	v_mov_b32_e32 v172, v131
	v_pk_add_f32 v[128:129], v[172:173], v[128:129]
	s_nop 0
	v_pk_fma_f32 v[128:129], v[128:129], s[2:3], v[198:199] op_sel_hi:[1,0,0]
	s_nop 0
	v_mul_f32_e32 v130, 0x4b800000, v129
	v_cmp_gt_f32_e64 s[0:1], s23, v129
	v_cmp_gt_f32_e32 vcc, s23, v128
	s_nop 0
	v_cndmask_b32_e64 v129, v129, v130, s[0:1]
	v_mul_f32_e32 v130, 0x4b800000, v128
	v_cndmask_b32_e32 v128, v128, v130, vcc
	v_rsq_f32_e32 v129, v129
	v_rsq_f32_e32 v128, v128
	s_nop 0
	v_pk_mul_f32 v[130:131], v[128:129], s[24:25] op_sel_hi:[1,0]
	s_nop 0
	v_cndmask_b32_e32 v173, v128, v130, vcc
	v_cndmask_b32_e64 v172, v129, v131, s[0:1]
	v_lshlrev_b64 v[128:129], 6, v[160:161]
	v_lshl_add_u64 v[140:141], s[20:21], 0, v[128:129]
	global_load_dwordx4 v[128:131], v[140:141], off offset:32
	global_load_dwordx4 v[132:135], v[140:141], off offset:48
	global_load_dwordx4 v[136:139], v[140:141], off
	s_nop 0
	global_load_dwordx4 v[140:143], v[140:141], off offset:16
	s_waitcnt vmcnt(0)
	v_pk_add_f32 v[128:129], v[128:129], v[132:133]
	v_pk_add_f32 v[130:131], v[130:131], v[134:135]
	v_pk_add_f32 v[136:137], v[136:137], v[140:141]
	v_pk_add_f32 v[138:139], v[138:139], v[142:143]
	v_pk_add_f32 v[184:185], v[136:137], v[128:129]
	v_lshlrev_b64 v[128:129], 6, v[158:159]
	v_lshl_add_u64 v[140:141], s[20:21], 0, v[128:129]
	v_pk_add_f32 v[174:175], v[138:139], v[130:131]
	global_load_dwordx4 v[128:131], v[140:141], off offset:32
	global_load_dwordx4 v[132:135], v[140:141], off offset:48
	global_load_dwordx4 v[136:139], v[140:141], off
	s_nop 0
	global_load_dwordx4 v[140:143], v[140:141], off offset:16
	s_waitcnt vmcnt(0)
	v_pk_add_f32 v[128:129], v[128:129], v[132:133]
	v_pk_add_f32 v[130:131], v[130:131], v[134:135]
	v_pk_add_f32 v[136:137], v[136:137], v[140:141]
	v_pk_add_f32 v[138:139], v[138:139], v[142:143]
	v_pk_add_f32 v[128:129], v[136:137], v[128:129]
	v_pk_add_f32 v[130:131], v[138:139], v[130:131]
	v_mov_b32_e32 v132, v128
	v_mov_b32_e32 v133, v184
	v_mov_b32_e32 v184, v129
	v_pk_add_f32 v[128:129], v[132:133], v[184:185]
	v_mov_b32_e32 v132, v130
	v_mov_b32_e32 v133, v174
	v_pk_add_f32 v[128:129], v[132:133], v[128:129]
	v_mov_b32_e32 v174, v131
	v_pk_add_f32 v[128:129], v[174:175], v[128:129]
	s_nop 0
	v_pk_fma_f32 v[128:129], v[128:129], s[2:3], v[198:199] op_sel_hi:[1,0,0]
	s_nop 0
	v_mul_f32_e32 v130, 0x4b800000, v129
	v_cmp_gt_f32_e64 s[0:1], s23, v129
	v_cmp_gt_f32_e32 vcc, s23, v128
	s_nop 0
	v_cndmask_b32_e64 v129, v129, v130, s[0:1]
	v_mul_f32_e32 v130, 0x4b800000, v128
	v_cndmask_b32_e32 v128, v128, v130, vcc
	v_rsq_f32_e32 v129, v129
	v_rsq_f32_e32 v128, v128
	s_nop 0
	v_pk_mul_f32 v[130:131], v[128:129], s[24:25] op_sel_hi:[1,0]
	s_nop 0
	v_cndmask_b32_e32 v175, v128, v130, vcc
	v_cndmask_b32_e64 v174, v129, v131, s[0:1]
	v_lshlrev_b64 v[128:129], 6, v[156:157]
	v_lshl_add_u64 v[140:141], s[20:21], 0, v[128:129]
	global_load_dwordx4 v[128:131], v[140:141], off offset:32
	global_load_dwordx4 v[132:135], v[140:141], off offset:48
	global_load_dwordx4 v[136:139], v[140:141], off
	s_nop 0
	global_load_dwordx4 v[140:143], v[140:141], off offset:16
	s_waitcnt vmcnt(0)
	v_pk_add_f32 v[128:129], v[128:129], v[132:133]
	v_pk_add_f32 v[130:131], v[130:131], v[134:135]
	v_pk_add_f32 v[136:137], v[136:137], v[140:141]
	v_pk_add_f32 v[138:139], v[138:139], v[142:143]
	v_pk_add_f32 v[202:203], v[136:137], v[128:129]
	v_lshlrev_b64 v[128:129], 6, v[154:155]
	v_lshl_add_u64 v[140:141], s[20:21], 0, v[128:129]
	v_pk_add_f32 v[200:201], v[138:139], v[130:131]
	global_load_dwordx4 v[128:131], v[140:141], off offset:32
	global_load_dwordx4 v[132:135], v[140:141], off offset:48
	global_load_dwordx4 v[136:139], v[140:141], off
	s_nop 0
	global_load_dwordx4 v[140:143], v[140:141], off offset:16
	s_waitcnt vmcnt(0)
	v_pk_add_f32 v[128:129], v[128:129], v[132:133]
	v_pk_add_f32 v[130:131], v[130:131], v[134:135]
	v_pk_add_f32 v[136:137], v[136:137], v[140:141]
	v_pk_add_f32 v[138:139], v[138:139], v[142:143]
	v_pk_add_f32 v[128:129], v[136:137], v[128:129]
	v_pk_add_f32 v[130:131], v[138:139], v[130:131]
	v_mov_b32_e32 v132, v128
	v_mov_b32_e32 v133, v202
	v_mov_b32_e32 v202, v129
	v_pk_add_f32 v[128:129], v[132:133], v[202:203]
	v_mov_b32_e32 v132, v130
	v_mov_b32_e32 v133, v200
	v_pk_add_f32 v[128:129], v[132:133], v[128:129]
	v_mov_b32_e32 v200, v131
	v_pk_add_f32 v[128:129], v[200:201], v[128:129]
	s_nop 0
	v_pk_fma_f32 v[128:129], v[128:129], s[2:3], v[198:199] op_sel_hi:[1,0,0]
	s_nop 0
	v_mul_f32_e32 v130, 0x4b800000, v129
	v_cmp_gt_f32_e64 s[0:1], s23, v129
	v_cmp_gt_f32_e32 vcc, s23, v128
	s_nop 0
	v_cndmask_b32_e64 v129, v129, v130, s[0:1]
	v_rsq_f32_e32 v131, v129
	v_mul_f32_e32 v129, 0x4b800000, v128
	v_cndmask_b32_e32 v128, v128, v129, vcc
	v_rsq_f32_e32 v130, v128
	s_nop 0
	v_pk_mul_f32 v[132:133], v[130:131], s[24:25] op_sel_hi:[1,0]
	s_nop 0
	v_cndmask_b32_e32 v129, v130, v132, vcc
	v_cndmask_b32_e64 v128, v131, v133, s[0:1]
	s_mov_b64 s[0:1], 0

.LBB0_170:
	s_add_u32 s20, s48, 0xfffc0080
	s_addc_u32 s21, s49, -1
	s_add_i32 s60, 0, 0x10000
	v_add_u32_e32 v140, s60, v232
	ds_read_b128 v[128:131], v140
	ds_read_b128 v[132:135], v140 offset:1024
	ds_read_b128 v[136:139], v140 offset:2048
	ds_read_b128 v[140:143], v140 offset:3072
	s_cmp_eq_u32 s57, 12
	s_cselect_b32 s51, s43, s21
	s_cselect_b32 s50, s24, s20
	s_cselect_b32 s29, s1, vcc_hi
	s_cselect_b32 s28, s25, vcc_lo
	v_lshl_add_u64 v[184:185], s[48:49], 0, v[204:205]
	s_add_i32 m0, s55, 0xc000
	ds_read_b128 v[144:147], v234
	ds_read_b128 v[148:151], v234 offset:1024
	ds_read_b128 v[152:155], v234 offset:2048
	ds_read_b128 v[156:159], v234 offset:3072
	ds_read_b128 v[160:163], v234 offset:4096
	ds_read_b128 v[164:167], v234 offset:5120
	ds_read_b128 v[168:171], v234 offset:6144
	ds_read_b128 v[172:175], v234 offset:7168
	global_load_lds_dwordx4 v[184:185], off
	v_lshl_add_u64 v[184:185], s[48:49], 0, v[206:207]
	s_add_i32 m0, s55, 0xe000
	s_nop 0
	global_load_lds_dwordx4 v[184:185], off
	s_waitcnt lgkmcnt(8)
	s_barrier
	s_waitcnt lgkmcnt(0)
	v_mfma_f32_16x16x32_bf16 v[124:127], v[128:131], v[144:147], v[124:127]
	v_mfma_f32_16x16x32_bf16 v[120:123], v[136:139], v[144:147], v[120:123]
	v_mfma_f32_16x16x32_bf16 v[108:111], v[128:131], v[152:155], v[108:111]
	v_mfma_f32_16x16x32_bf16 v[104:107], v[136:139], v[152:155], v[104:107]
	v_mfma_f32_16x16x32_bf16 v[92:95], v[128:131], v[160:163], v[92:95]
	v_mfma_f32_16x16x32_bf16 v[88:91], v[136:139], v[160:163], v[88:91]
	v_mfma_f32_16x16x32_bf16 v[76:79], v[128:131], v[168:171], v[76:79]
	v_mfma_f32_16x16x32_bf16 v[72:75], v[136:139], v[168:171], v[72:75]
	v_mfma_f32_16x16x32_bf16 v[124:127], v[132:135], v[148:151], v[124:127]
	v_mfma_f32_16x16x32_bf16 v[120:123], v[140:143], v[148:151], v[120:123]
	v_mfma_f32_16x16x32_bf16 v[108:111], v[132:135], v[156:159], v[108:111]
	v_mfma_f32_16x16x32_bf16 v[104:107], v[140:143], v[156:159], v[104:107]
	v_mfma_f32_16x16x32_bf16 v[92:95], v[132:135], v[164:167], v[92:95]
	v_mfma_f32_16x16x32_bf16 v[88:91], v[140:143], v[164:167], v[88:91]
	v_mfma_f32_16x16x32_bf16 v[76:79], v[132:135], v[172:175], v[76:79]
	v_mfma_f32_16x16x32_bf16 v[72:75], v[140:143], v[172:175], v[72:75]
	s_barrier
	s_add_i32 s61, 0, 0x14000
	v_add_u32_e32 v184, s61, v232
	s_add_i32 s20, s60, s54
	ds_read_b128 v[208:211], v184
	ds_read_b128 v[212:215], v184 offset:1024
	ds_read_b128 v[216:219], v184 offset:2048
	ds_read_b128 v[236:239], v184 offset:3072
	v_lshl_add_u64 v[184:185], s[28:29], 0, v[176:177]
	s_mov_b32 m0, s20
	v_lshl_add_u64 v[192:193], s[28:29], 0, v[198:199]
	global_load_lds_dwordx4 v[184:185], off
	s_add_i32 m0, s20, 0x2000
	s_nop 0
	global_load_lds_dwordx4 v[192:193], off
	s_barrier
	s_waitcnt lgkmcnt(0)
	v_mfma_f32_16x16x32_bf16 v[116:119], v[208:211], v[144:147], v[116:119]
	v_mfma_f32_16x16x32_bf16 v[112:115], v[216:219], v[144:147], v[112:115]
	v_mfma_f32_16x16x32_bf16 v[100:103], v[208:211], v[152:155], v[100:103]
	v_mfma_f32_16x16x32_bf16 v[96:99], v[216:219], v[152:155], v[96:99]
	v_mfma_f32_16x16x32_bf16 v[84:87], v[208:211], v[160:163], v[84:87]
	v_mfma_f32_16x16x32_bf16 v[80:83], v[216:219], v[160:163], v[80:83]
	v_mfma_f32_16x16x32_bf16 v[68:71], v[208:211], v[168:171], v[68:71]
	v_mfma_f32_16x16x32_bf16 v[64:67], v[216:219], v[168:171], v[64:67]
	v_mfma_f32_16x16x32_bf16 v[116:119], v[212:215], v[148:151], v[116:119]
	v_mfma_f32_16x16x32_bf16 v[112:115], v[236:239], v[148:151], v[112:115]
	v_mfma_f32_16x16x32_bf16 v[100:103], v[212:215], v[156:159], v[100:103]
	v_mfma_f32_16x16x32_bf16 v[96:99], v[236:239], v[156:159], v[96:99]
	v_mfma_f32_16x16x32_bf16 v[84:87], v[212:215], v[164:167], v[84:87]
	v_mfma_f32_16x16x32_bf16 v[80:83], v[236:239], v[164:167], v[80:83]
	v_mfma_f32_16x16x32_bf16 v[68:71], v[212:215], v[172:175], v[68:71]
	v_mfma_f32_16x16x32_bf16 v[64:67], v[236:239], v[172:175], v[64:67]
	s_mov_b32 m0, s55
	v_lshl_add_u64 v[194:195], s[50:51], 0, v[202:203]
	s_barrier
	ds_read_b128 v[144:147], v234 offset:16384
	ds_read_b128 v[148:151], v234 offset:17408
	ds_read_b128 v[152:155], v234 offset:18432
	ds_read_b128 v[156:159], v234 offset:19456
	ds_read_b128 v[160:163], v234 offset:20480
	ds_read_b128 v[164:167], v234 offset:21504
	ds_read_b128 v[168:171], v234 offset:22528
	ds_read_b128 v[172:175], v234 offset:23552
	global_load_lds_dwordx4 v[194:195], off
	v_lshl_add_u64 v[240:241], s[50:51], 0, v[200:201]
	s_mov_b32 m0, s56
	s_nop 0
	global_load_lds_dwordx4 v[240:241], off
	s_barrier
	s_waitcnt lgkmcnt(0)
	v_mfma_f32_16x16x32_bf16 v[60:63], v[128:131], v[144:147], v[60:63]
	v_mfma_f32_16x16x32_bf16 v[56:59], v[136:139], v[144:147], v[56:59]
	v_mfma_f32_16x16x32_bf16 v[44:47], v[128:131], v[152:155], v[44:47]
	v_mfma_f32_16x16x32_bf16 v[40:43], v[136:139], v[152:155], v[40:43]
	v_mfma_f32_16x16x32_bf16 v[28:31], v[128:131], v[160:163], v[28:31]
	v_mfma_f32_16x16x32_bf16 v[24:27], v[136:139], v[160:163], v[24:27]
	v_mfma_f32_16x16x32_bf16 v[12:15], v[128:131], v[168:171], v[12:15]
	v_mfma_f32_16x16x32_bf16 v[8:11], v[136:139], v[168:171], v[8:11]
	v_mfma_f32_16x16x32_bf16 v[60:63], v[132:135], v[148:151], v[60:63]
	v_mfma_f32_16x16x32_bf16 v[56:59], v[140:143], v[148:151], v[56:59]
	v_mfma_f32_16x16x32_bf16 v[44:47], v[132:135], v[156:159], v[44:47]
	v_mfma_f32_16x16x32_bf16 v[40:43], v[140:143], v[156:159], v[40:43]
	v_mfma_f32_16x16x32_bf16 v[28:31], v[132:135], v[164:167], v[28:31]
	v_mfma_f32_16x16x32_bf16 v[24:27], v[140:143], v[164:167], v[24:27]
	v_mfma_f32_16x16x32_bf16 v[12:15], v[132:135], v[172:175], v[12:15]
	v_mfma_f32_16x16x32_bf16 v[8:11], v[140:143], v[172:175], v[8:11]
	s_barrier
	s_add_u32 s20, s28, 0x40000
	s_addc_u32 s21, s29, 0
	s_add_i32 s60, s61, s54
	v_lshl_add_u64 v[128:129], s[20:21], 0, v[176:177]
	s_mov_b32 m0, s60
	s_nop 0
	global_load_lds_dwordx4 v[128:129], off
	v_lshl_add_u64 v[128:129], s[20:21], 0, v[198:199]
	s_add_i32 m0, s60, 0x2000
	s_nop 0
	global_load_lds_dwordx4 v[128:129], off
	s_waitcnt vmcnt(6)
	s_barrier
	v_mfma_f32_16x16x32_bf16 v[52:55], v[208:211], v[144:147], v[52:55]
	v_mfma_f32_16x16x32_bf16 v[48:51], v[216:219], v[144:147], v[48:51]
	v_mfma_f32_16x16x32_bf16 v[36:39], v[208:211], v[152:155], v[36:39]
	v_mfma_f32_16x16x32_bf16 v[32:35], v[216:219], v[152:155], v[32:35]
	v_mfma_f32_16x16x32_bf16 v[20:23], v[208:211], v[160:163], v[20:23]
	v_mfma_f32_16x16x32_bf16 v[16:19], v[216:219], v[160:163], v[16:19]
	v_mfma_f32_16x16x32_bf16 v[4:7], v[208:211], v[168:171], v[4:7]
	v_mfma_f32_16x16x32_bf16 v[0:3], v[216:219], v[168:171], v[0:3]
	v_mfma_f32_16x16x32_bf16 v[52:55], v[212:215], v[148:151], v[52:55]
	v_mfma_f32_16x16x32_bf16 v[48:51], v[236:239], v[148:151], v[48:51]
	v_mfma_f32_16x16x32_bf16 v[36:39], v[212:215], v[156:159], v[36:39]
	v_mfma_f32_16x16x32_bf16 v[32:35], v[236:239], v[156:159], v[32:35]
	v_mfma_f32_16x16x32_bf16 v[20:23], v[212:215], v[164:167], v[20:23]
	v_mfma_f32_16x16x32_bf16 v[16:19], v[236:239], v[164:167], v[16:19]
	v_mfma_f32_16x16x32_bf16 v[4:7], v[212:215], v[172:175], v[4:7]
	v_mfma_f32_16x16x32_bf16 v[0:3], v[236:239], v[172:175], v[0:3]
	s_add_i32 s60, 0, 0x18000
	v_add_u32_e32 v140, s60, v232
	s_barrier
	ds_read_b128 v[128:131], v140
	ds_read_b128 v[132:135], v140 offset:1024
	ds_read_b128 v[136:139], v140 offset:2048
	ds_read_b128 v[140:143], v140 offset:3072
	s_add_u32 s20, s50, 0x40000
	s_addc_u32 s21, s51, 0
	s_mov_b32 m0, s7
	v_lshl_add_u64 v[208:209], s[20:21], 0, v[202:203]
	ds_read_b128 v[144:147], v234 offset:32768
	ds_read_b128 v[148:151], v234 offset:33792
	ds_read_b128 v[152:155], v234 offset:34816
	ds_read_b128 v[156:159], v234 offset:35840
	ds_read_b128 v[160:163], v234 offset:36864
	ds_read_b128 v[164:167], v234 offset:37888
	ds_read_b128 v[168:171], v234 offset:38912
	ds_read_b128 v[172:175], v234 offset:39936
	global_load_lds_dwordx4 v[208:209], off
	v_lshl_add_u64 v[208:209], s[20:21], 0, v[200:201]
	s_mov_b32 m0, s15
	s_nop 0
	global_load_lds_dwordx4 v[208:209], off
	s_waitcnt lgkmcnt(8)
	s_barrier
	s_waitcnt lgkmcnt(0)
	v_mfma_f32_16x16x32_bf16 v[124:127], v[128:131], v[144:147], v[124:127]
	v_mfma_f32_16x16x32_bf16 v[120:123], v[136:139], v[144:147], v[120:123]
	v_mfma_f32_16x16x32_bf16 v[108:111], v[128:131], v[152:155], v[108:111]
	v_mfma_f32_16x16x32_bf16 v[104:107], v[136:139], v[152:155], v[104:107]
	v_mfma_f32_16x16x32_bf16 v[92:95], v[128:131], v[160:163], v[92:95]
	v_mfma_f32_16x16x32_bf16 v[88:91], v[136:139], v[160:163], v[88:91]
	v_mfma_f32_16x16x32_bf16 v[76:79], v[128:131], v[168:171], v[76:79]
	v_mfma_f32_16x16x32_bf16 v[72:75], v[136:139], v[168:171], v[72:75]
	v_mfma_f32_16x16x32_bf16 v[124:127], v[132:135], v[148:151], v[124:127]
	v_mfma_f32_16x16x32_bf16 v[120:123], v[140:143], v[148:151], v[120:123]
	v_mfma_f32_16x16x32_bf16 v[108:111], v[132:135], v[156:159], v[108:111]
	v_mfma_f32_16x16x32_bf16 v[104:107], v[140:143], v[156:159], v[104:107]
	v_mfma_f32_16x16x32_bf16 v[92:95], v[132:135], v[164:167], v[92:95]
	v_mfma_f32_16x16x32_bf16 v[88:91], v[140:143], v[164:167], v[88:91]
	v_mfma_f32_16x16x32_bf16 v[76:79], v[132:135], v[172:175], v[76:79]
	v_mfma_f32_16x16x32_bf16 v[72:75], v[140:143], v[172:175], v[72:75]
	s_barrier
	s_add_i32 s50, 0, 0x1c000
	s_add_i32 s20, s60, s54
	v_add_u32_e32 v235, s50, v232
	v_lshl_add_u64 v[184:185], v[184:185], 0, s[52:53]
	s_mov_b32 m0, s20
	ds_read_b128 v[208:211], v235
	ds_read_b128 v[212:215], v235 offset:1024
	ds_read_b128 v[216:219], v235 offset:2048
	ds_read_b128 v[236:239], v235 offset:3072
	global_load_lds_dwordx4 v[184:185], off
	v_lshl_add_u64 v[184:185], v[192:193], 0, s[52:53]
	s_add_i32 m0, s20, 0x2000
	s_nop 0
	global_load_lds_dwordx4 v[184:185], off
	s_barrier
	s_waitcnt lgkmcnt(0)
	v_mfma_f32_16x16x32_bf16 v[116:119], v[208:211], v[144:147], v[116:119]
	v_mfma_f32_16x16x32_bf16 v[112:115], v[216:219], v[144:147], v[112:115]
	v_mfma_f32_16x16x32_bf16 v[100:103], v[208:211], v[152:155], v[100:103]
	v_mfma_f32_16x16x32_bf16 v[96:99], v[216:219], v[152:155], v[96:99]
	v_mfma_f32_16x16x32_bf16 v[84:87], v[208:211], v[160:163], v[84:87]
	v_mfma_f32_16x16x32_bf16 v[80:83], v[216:219], v[160:163], v[80:83]
	v_mfma_f32_16x16x32_bf16 v[68:71], v[208:211], v[168:171], v[68:71]
	v_mfma_f32_16x16x32_bf16 v[64:67], v[216:219], v[168:171], v[64:67]
	v_mfma_f32_16x16x32_bf16 v[116:119], v[212:215], v[148:151], v[116:119]
	v_mfma_f32_16x16x32_bf16 v[112:115], v[236:239], v[148:151], v[112:115]
	v_mfma_f32_16x16x32_bf16 v[100:103], v[212:215], v[156:159], v[100:103]
	v_mfma_f32_16x16x32_bf16 v[96:99], v[236:239], v[156:159], v[96:99]
	v_mfma_f32_16x16x32_bf16 v[84:87], v[212:215], v[164:167], v[84:87]
	v_mfma_f32_16x16x32_bf16 v[80:83], v[236:239], v[164:167], v[80:83]
	v_mfma_f32_16x16x32_bf16 v[68:71], v[212:215], v[172:175], v[68:71]
	v_mfma_f32_16x16x32_bf16 v[64:67], v[236:239], v[172:175], v[64:67]
	s_mov_b32 m0, s3
	v_lshl_add_u64 v[184:185], v[194:195], 0, s[52:53]
	s_barrier
	ds_read_b128 v[144:147], v234 offset:49152
	ds_read_b128 v[148:151], v234 offset:50176
	ds_read_b128 v[152:155], v234 offset:51200
	ds_read_b128 v[156:159], v234 offset:52224
	ds_read_b128 v[160:163], v234 offset:53248
	ds_read_b128 v[164:167], v234 offset:54272
	ds_read_b128 v[168:171], v234 offset:55296
	ds_read_b128 v[172:175], v234 offset:56320
	global_load_lds_dwordx4 v[184:185], off
	v_lshl_add_u64 v[184:185], v[240:241], 0, s[52:53]
	s_mov_b32 m0, s6
	s_nop 0
	global_load_lds_dwordx4 v[184:185], off
	s_barrier
	s_waitcnt lgkmcnt(0)
	v_mfma_f32_16x16x32_bf16 v[60:63], v[128:131], v[144:147], v[60:63]
	v_mfma_f32_16x16x32_bf16 v[56:59], v[136:139], v[144:147], v[56:59]
	v_mfma_f32_16x16x32_bf16 v[44:47], v[128:131], v[152:155], v[44:47]
	v_mfma_f32_16x16x32_bf16 v[40:43], v[136:139], v[152:155], v[40:43]
	v_mfma_f32_16x16x32_bf16 v[28:31], v[128:131], v[160:163], v[28:31]
	v_mfma_f32_16x16x32_bf16 v[24:27], v[136:139], v[160:163], v[24:27]
	v_mfma_f32_16x16x32_bf16 v[12:15], v[128:131], v[168:171], v[12:15]
	v_mfma_f32_16x16x32_bf16 v[8:11], v[136:139], v[168:171], v[8:11]
	v_mfma_f32_16x16x32_bf16 v[60:63], v[132:135], v[148:151], v[60:63]
	v_mfma_f32_16x16x32_bf16 v[56:59], v[140:143], v[148:151], v[56:59]
	v_mfma_f32_16x16x32_bf16 v[44:47], v[132:135], v[156:159], v[44:47]
	v_mfma_f32_16x16x32_bf16 v[40:43], v[140:143], v[156:159], v[40:43]
	v_mfma_f32_16x16x32_bf16 v[28:31], v[132:135], v[164:167], v[28:31]
	v_mfma_f32_16x16x32_bf16 v[24:27], v[140:143], v[164:167], v[24:27]
	v_mfma_f32_16x16x32_bf16 v[12:15], v[132:135], v[172:175], v[12:15]
	v_mfma_f32_16x16x32_bf16 v[8:11], v[140:143], v[172:175], v[8:11]
	s_barrier
	s_add_u32 s20, s28, 0x40080
	s_addc_u32 s21, s29, 0
	s_add_i32 s28, s50, s54
	v_lshl_add_u64 v[128:129], s[20:21], 0, v[176:177]
	s_mov_b32 m0, s28
	s_nop 0
	global_load_lds_dwordx4 v[128:129], off
	v_lshl_add_u64 v[128:129], s[20:21], 0, v[198:199]
	s_add_i32 m0, s28, 0x2000
	s_nop 0
	global_load_lds_dwordx4 v[128:129], off
	s_waitcnt vmcnt(6)
	s_barrier
	v_mfma_f32_16x16x32_bf16 v[52:55], v[208:211], v[144:147], v[52:55]
	v_mfma_f32_16x16x32_bf16 v[48:51], v[216:219], v[144:147], v[48:51]
	v_mfma_f32_16x16x32_bf16 v[36:39], v[208:211], v[152:155], v[36:39]
	v_mfma_f32_16x16x32_bf16 v[32:35], v[216:219], v[152:155], v[32:35]
	v_mfma_f32_16x16x32_bf16 v[20:23], v[208:211], v[160:163], v[20:23]
	v_mfma_f32_16x16x32_bf16 v[16:19], v[216:219], v[160:163], v[16:19]
	v_mfma_f32_16x16x32_bf16 v[4:7], v[208:211], v[168:171], v[4:7]
	v_mfma_f32_16x16x32_bf16 v[0:3], v[216:219], v[168:171], v[0:3]
	v_mfma_f32_16x16x32_bf16 v[52:55], v[212:215], v[148:151], v[52:55]
	v_mfma_f32_16x16x32_bf16 v[48:51], v[236:239], v[148:151], v[48:51]
	v_mfma_f32_16x16x32_bf16 v[36:39], v[212:215], v[156:159], v[36:39]
	v_mfma_f32_16x16x32_bf16 v[32:35], v[236:239], v[156:159], v[32:35]
	v_mfma_f32_16x16x32_bf16 v[20:23], v[212:215], v[164:167], v[20:23]
	v_mfma_f32_16x16x32_bf16 v[16:19], v[236:239], v[164:167], v[16:19]
	v_mfma_f32_16x16x32_bf16 v[4:7], v[212:215], v[172:175], v[4:7]
	v_mfma_f32_16x16x32_bf16 v[0:3], v[236:239], v[172:175], v[0:3]
	s_add_i32 s57, s57, 2
	s_add_u32 s48, s48, 0x100
	s_addc_u32 s49, s49, 0
	s_add_u32 vcc_lo, vcc_lo, 0x100
	s_addc_u32 vcc_hi, vcc_hi, 0
	s_cmp_gt_u32 s57, 13
	s_barrier
	s_cbranch_scc0 .LBB0_170
	v_lshl_add_u32 v210, s2, 8, v231
	v_lshl_or_b32 v208, s34, 8, v233
	v_readlane_b32 s60, v252, 10
	v_ashrrev_i32_e32 v209, 31, v208
	v_readlane_b32 s61, v252, 11
	v_ashrrev_i32_e32 v211, 31, v210
	v_lshlrev_b64 v[128:129], 12, v[210:211]
	v_lshl_add_u64 v[212:213], v[208:209], 2, s[60:61]
	v_lshl_add_u64 v[128:129], v[212:213], 0, v[128:129]
	global_load_dwordx4 v[236:239], v[128:129], off offset:16
	global_load_dwordx4 v[240:243], v[128:129], off
	global_load_dwordx4 v[244:247], v[128:129], off offset:528
	global_load_dwordx4 v[248:251], v[128:129], off offset:512
	v_or_b32_e32 v218, 16, v210
	v_ashrrev_i32_e32 v219, 31, v218
	v_lshlrev_b64 v[128:129], 12, v[218:219]
	v_or_b32_e32 v216, 32, v210
	v_lshl_add_u64 v[128:129], v[212:213], 0, v[128:129]
	v_ashrrev_i32_e32 v217, 31, v216
	global_load_dwordx4 v[168:171], v[128:129], off offset:16
	global_load_dwordx4 v[172:175], v[128:129], off
	global_load_dwordx4 v[160:163], v[128:129], off offset:528
	global_load_dwordx4 v[164:167], v[128:129], off offset:512
	v_lshlrev_b64 v[128:129], 12, v[216:217]
	v_or_b32_e32 v214, 48, v210
	v_lshl_add_u64 v[128:129], v[212:213], 0, v[128:129]
	v_ashrrev_i32_e32 v215, 31, v214
	global_load_dwordx4 v[152:155], v[128:129], off offset:16
	global_load_dwordx4 v[156:159], v[128:129], off
	global_load_dwordx4 v[136:139], v[128:129], off offset:528
	global_load_dwordx4 v[144:147], v[128:129], off offset:512
	v_lshlrev_b64 v[128:129], 12, v[214:215]
	v_lshl_add_u64 v[132:133], v[212:213], 0, v[128:129]
	global_load_dwordx4 v[140:143], v[132:133], off offset:16
	global_load_dwordx4 v[148:151], v[132:133], off
	global_load_dwordx4 v[128:131], v[132:133], off offset:528
	s_nop 0
	global_load_dwordx4 v[132:135], v[132:133], off offset:512
	v_readlane_b32 s68, v252, 18
	v_readlane_b32 s69, v252, 19
	v_readlane_b32 s68, v255, 14
	v_readlane_b32 s69, v255, 15
	s_lshl_b32 s48, s34, 2
	s_ashr_i32 s49, s48, 31
	v_readlane_b32 s62, v252, 12
	v_readlane_b32 s63, v252, 13
	v_readlane_b32 s64, v252, 14
	v_readlane_b32 s65, v252, 15
	v_readlane_b32 s66, v252, 16
	v_readlane_b32 s67, v252, 17
	v_readlane_b32 s70, v252, 20
	v_readlane_b32 s71, v252, 21
	v_readlane_b32 s72, v252, 22
	v_readlane_b32 s73, v252, 23
	v_readlane_b32 s74, v252, 24
	v_readlane_b32 s75, v252, 25
	s_waitcnt vmcnt(0)
	v_pk_add_f32 v[184:185], v[122:123], v[238:239]
	v_pk_add_f32 v[122:123], v[120:121], v[236:237]
	v_pk_add_f32 v[124:125], v[124:125], v[240:241]
	v_mul_f32_e32 v120, v122, v122
	v_mul_f32_e32 v121, v123, v123
	v_fmac_f32_e32 v120, v124, v124
	v_fmac_f32_e32 v121, v125, v125
	v_pk_add_f32 v[126:127], v[126:127], v[242:243]
	v_add_f32_e32 v120, v120, v121
	v_mul_f32_e32 v121, v184, v184
	v_fmac_f32_e32 v121, v126, v126
	v_add_f32_e32 v120, v121, v120
	v_mul_f32_e32 v121, v185, v185
	v_fmac_f32_e32 v121, v127, v127
	v_add_f32_e32 v192, v121, v120
	v_cvt_pk_bf16_f32 v120, v124, v125
	v_lshlrev_b64 v[124:125], 11, v[210:211]
	v_lshl_add_u64 v[124:125], s[68:69], 0, v[124:125]
	v_cvt_pk_bf16_f32 v121, v126, v127
	v_lshl_add_u64 v[124:125], v[208:209], 1, v[124:125]
	v_cvt_pk_bf16_f32 v122, v122, v123
	v_cvt_pk_bf16_f32 v123, v184, v185
	global_store_dwordx4 v[124:125], v[120:123], off
	v_pk_add_f32 v[116:117], v[116:117], v[248:249]
	v_pk_add_f32 v[118:119], v[118:119], v[250:251]
	v_pk_add_f32 v[120:121], v[114:115], v[246:247]
	v_pk_add_f32 v[114:115], v[112:113], v[244:245]
	s_nop 0
	v_mul_f32_e32 v112, v114, v114
	v_fmac_f32_e32 v112, v116, v116
	v_mul_f32_e32 v113, v115, v115
	v_add_f32_e32 v112, v112, v192
	v_fmac_f32_e32 v113, v117, v117
	v_add_f32_e32 v112, v113, v112
	v_mul_f32_e32 v113, v120, v120
	v_fmac_f32_e32 v113, v118, v118
	v_add_f32_e32 v112, v113, v112
	v_mul_f32_e32 v113, v121, v121
	v_fmac_f32_e32 v113, v119, v119
	v_add_f32_e32 v122, v113, v112
	v_cvt_pk_bf16_f32 v112, v116, v117
	v_cvt_pk_bf16_f32 v113, v118, v119
	v_cvt_pk_bf16_f32 v114, v114, v115
	v_cvt_pk_bf16_f32 v115, v120, v121
	global_store_dwordx4 v[124:125], v[112:115], off offset:256
	s_nop 1
	v_and_b32_e32 v113, 64, v225
	v_xor_b32_e32 v112, 16, v225
	v_add_u32_e32 v113, 64, v113
	v_cmp_lt_i32_e32 vcc, v112, v113
	v_xor_b32_e32 v114, 32, v225
	s_nop 0
	v_cndmask_b32_e32 v112, v225, v112, vcc
	v_lshlrev_b32_e32 v235, 2, v112
	ds_bpermute_b32 v112, v235, v122
	v_cmp_lt_i32_e32 vcc, v114, v113
	s_waitcnt lgkmcnt(0)
	v_add_f32_e32 v112, v122, v112
	v_cndmask_b32_e32 v113, v225, v114, vcc
	v_lshlrev_b32_e32 v236, 2, v113
	ds_bpermute_b32 v113, v236, v112
	s_and_saveexec_b64 s[28:29], s[38:39]
	s_cbranch_execz .LBB0_173
	v_readlane_b32 s20, v253, 31
	v_lshlrev_b64 v[114:115], 6, v[210:211]
	v_readlane_b32 s21, v253, 32
	s_lshl_b32 s34, s58, 2
	s_waitcnt lgkmcnt(0)
	v_add_f32_e32 v112, v112, v113
	v_lshl_add_u64 v[114:115], s[20:21], 0, v[114:115]
	v_lshl_add_u64 v[114:115], s[48:49], 2, v[114:115]
	v_lshl_add_u64 v[114:115], v[114:115], 0, s[34:35]
	global_store_dword v[114:115], v112, off

.LBB0_292:
	s_add_u32 s20, s46, 0xfffc0080
	s_addc_u32 s21, s47, -1
	s_add_i32 s60, 0, 0x10000
	v_add_u32_e32 v138, s60, v141
	ds_read_b128 v[144:147], v138
	ds_read_b128 v[148:151], v138 offset:1024
	ds_read_b128 v[152:155], v138 offset:2048
	ds_read_b128 v[156:159], v138 offset:3072
	s_cmp_eq_u32 vcc_lo, 12
	s_cselect_b32 s49, s41, s21
	s_cselect_b32 s48, s24, s20
	s_cselect_b32 s29, s1, s59
	s_cselect_b32 s28, s25, s58
	v_lshl_add_u64 v[138:139], s[46:47], 0, v[134:135]
	s_add_i32 m0, s7, 0xc000
	ds_read_b128 v[160:163], v143
	ds_read_b128 v[164:167], v143 offset:1024
	ds_read_b128 v[168:171], v143 offset:2048
	ds_read_b128 v[172:175], v143 offset:3072
	ds_read_b128 v[198:201], v143 offset:4096
	ds_read_b128 v[202:205], v143 offset:5120
	ds_read_b128 v[206:209], v143 offset:6144
	ds_read_b128 v[210:213], v143 offset:7168
	global_load_lds_dwordx4 v[138:139], off
	v_lshl_add_u64 v[138:139], s[46:47], 0, v[136:137]
	s_add_i32 m0, s7, 0xe000
	s_nop 0
	global_load_lds_dwordx4 v[138:139], off
	s_waitcnt lgkmcnt(8)
	s_barrier
	s_waitcnt lgkmcnt(0)
	v_mfma_f32_16x16x32_bf16 v[124:127], v[144:147], v[160:163], v[124:127]
	v_mfma_f32_16x16x32_bf16 v[120:123], v[152:155], v[160:163], v[120:123]
	v_mfma_f32_16x16x32_bf16 v[116:119], v[144:147], v[168:171], v[116:119]
	v_mfma_f32_16x16x32_bf16 v[108:111], v[152:155], v[168:171], v[108:111]
	v_mfma_f32_16x16x32_bf16 v[100:103], v[144:147], v[198:201], v[100:103]
	v_mfma_f32_16x16x32_bf16 v[92:95], v[152:155], v[198:201], v[92:95]
	v_mfma_f32_16x16x32_bf16 v[80:83], v[144:147], v[206:209], v[80:83]
	v_mfma_f32_16x16x32_bf16 v[72:75], v[152:155], v[206:209], v[72:75]
	v_mfma_f32_16x16x32_bf16 v[124:127], v[148:151], v[164:167], v[124:127]
	v_mfma_f32_16x16x32_bf16 v[120:123], v[156:159], v[164:167], v[120:123]
	v_mfma_f32_16x16x32_bf16 v[116:119], v[148:151], v[172:175], v[116:119]
	v_mfma_f32_16x16x32_bf16 v[108:111], v[156:159], v[172:175], v[108:111]
	v_mfma_f32_16x16x32_bf16 v[100:103], v[148:151], v[202:205], v[100:103]
	v_mfma_f32_16x16x32_bf16 v[92:95], v[156:159], v[202:205], v[92:95]
	v_mfma_f32_16x16x32_bf16 v[80:83], v[148:151], v[210:213], v[80:83]
	v_mfma_f32_16x16x32_bf16 v[72:75], v[156:159], v[210:213], v[72:75]
	s_barrier
	s_add_i32 s61, 0, 0x14000
	v_add_u32_e32 v138, s61, v141
	s_add_i32 s20, s60, s6
	ds_read_b128 v[214:217], v138
	ds_read_b128 v[232:235], v138 offset:1024
	ds_read_b128 v[236:239], v138 offset:2048
	ds_read_b128 v[240:243], v138 offset:3072
	v_lshl_add_u64 v[138:139], s[28:29], 0, v[176:177]
	s_mov_b32 m0, s20
	v_lshl_add_u64 v[218:219], s[28:29], 0, v[128:129]
	global_load_lds_dwordx4 v[138:139], off
	s_add_i32 m0, s20, 0x2000
	s_nop 0
	global_load_lds_dwordx4 v[218:219], off
	s_barrier
	s_waitcnt lgkmcnt(0)
	v_mfma_f32_16x16x32_bf16 v[112:115], v[214:217], v[160:163], v[112:115]
	v_mfma_f32_16x16x32_bf16 v[104:107], v[236:239], v[160:163], v[104:107]
	v_mfma_f32_16x16x32_bf16 v[96:99], v[214:217], v[168:171], v[96:99]
	v_mfma_f32_16x16x32_bf16 v[88:91], v[236:239], v[168:171], v[88:91]
	v_mfma_f32_16x16x32_bf16 v[84:87], v[214:217], v[198:201], v[84:87]
	v_mfma_f32_16x16x32_bf16 v[76:79], v[236:239], v[198:201], v[76:79]
	v_mfma_f32_16x16x32_bf16 v[68:71], v[214:217], v[206:209], v[68:71]
	v_mfma_f32_16x16x32_bf16 v[64:67], v[236:239], v[206:209], v[64:67]
	v_mfma_f32_16x16x32_bf16 v[112:115], v[232:235], v[164:167], v[112:115]
	v_mfma_f32_16x16x32_bf16 v[104:107], v[240:243], v[164:167], v[104:107]
	v_mfma_f32_16x16x32_bf16 v[96:99], v[232:235], v[172:175], v[96:99]
	v_mfma_f32_16x16x32_bf16 v[88:91], v[240:243], v[172:175], v[88:91]
	v_mfma_f32_16x16x32_bf16 v[84:87], v[232:235], v[202:205], v[84:87]
	v_mfma_f32_16x16x32_bf16 v[76:79], v[240:243], v[202:205], v[76:79]
	v_mfma_f32_16x16x32_bf16 v[68:71], v[232:235], v[210:213], v[68:71]
	v_mfma_f32_16x16x32_bf16 v[64:67], v[240:243], v[210:213], v[64:67]
	s_mov_b32 m0, s7
	v_lshl_add_u64 v[244:245], s[48:49], 0, v[132:133]
	s_barrier
	ds_read_b128 v[160:163], v143 offset:16384
	ds_read_b128 v[164:167], v143 offset:17408
	ds_read_b128 v[168:171], v143 offset:18432
	ds_read_b128 v[172:175], v143 offset:19456
	ds_read_b128 v[198:201], v143 offset:20480
	ds_read_b128 v[202:205], v143 offset:21504
	ds_read_b128 v[206:209], v143 offset:22528
	ds_read_b128 v[210:213], v143 offset:23552
	global_load_lds_dwordx4 v[244:245], off
	v_lshl_add_u64 v[246:247], s[48:49], 0, v[130:131]
	s_mov_b32 m0, s9
	s_nop 0
	global_load_lds_dwordx4 v[246:247], off
	s_barrier
	s_waitcnt lgkmcnt(0)
	v_mfma_f32_16x16x32_bf16 v[60:63], v[144:147], v[160:163], v[60:63]
	v_mfma_f32_16x16x32_bf16 v[56:59], v[152:155], v[160:163], v[56:59]
	v_mfma_f32_16x16x32_bf16 v[52:55], v[144:147], v[168:171], v[52:55]
	v_mfma_f32_16x16x32_bf16 v[44:47], v[152:155], v[168:171], v[44:47]
	v_mfma_f32_16x16x32_bf16 v[36:39], v[144:147], v[198:201], v[36:39]
	v_mfma_f32_16x16x32_bf16 v[28:31], v[152:155], v[198:201], v[28:31]
	v_mfma_f32_16x16x32_bf16 v[20:23], v[144:147], v[206:209], v[20:23]
	v_mfma_f32_16x16x32_bf16 v[12:15], v[152:155], v[206:209], v[12:15]
	v_mfma_f32_16x16x32_bf16 v[60:63], v[148:151], v[164:167], v[60:63]
	v_mfma_f32_16x16x32_bf16 v[56:59], v[156:159], v[164:167], v[56:59]
	v_mfma_f32_16x16x32_bf16 v[52:55], v[148:151], v[172:175], v[52:55]
	v_mfma_f32_16x16x32_bf16 v[44:47], v[156:159], v[172:175], v[44:47]
	v_mfma_f32_16x16x32_bf16 v[36:39], v[148:151], v[202:205], v[36:39]
	v_mfma_f32_16x16x32_bf16 v[28:31], v[156:159], v[202:205], v[28:31]
	v_mfma_f32_16x16x32_bf16 v[20:23], v[148:151], v[210:213], v[20:23]
	v_mfma_f32_16x16x32_bf16 v[12:15], v[156:159], v[210:213], v[12:15]
	s_barrier
	s_add_u32 s20, s28, 0x40000
	s_addc_u32 s21, s29, 0
	s_add_i32 s60, s61, s6
	v_lshl_add_u64 v[144:145], s[20:21], 0, v[176:177]
	s_mov_b32 m0, s60
	s_nop 0
	global_load_lds_dwordx4 v[144:145], off
	v_lshl_add_u64 v[144:145], s[20:21], 0, v[128:129]
	s_add_i32 m0, s60, 0x2000
	s_nop 0
	global_load_lds_dwordx4 v[144:145], off
	s_waitcnt vmcnt(6)
	s_barrier
	v_mfma_f32_16x16x32_bf16 v[48:51], v[214:217], v[160:163], v[48:51]
	v_mfma_f32_16x16x32_bf16 v[40:43], v[236:239], v[160:163], v[40:43]
	v_mfma_f32_16x16x32_bf16 v[32:35], v[214:217], v[168:171], v[32:35]
	v_mfma_f32_16x16x32_bf16 v[24:27], v[236:239], v[168:171], v[24:27]
	v_mfma_f32_16x16x32_bf16 v[16:19], v[214:217], v[198:201], v[16:19]
	v_mfma_f32_16x16x32_bf16 v[8:11], v[236:239], v[198:201], v[8:11]
	v_mfma_f32_16x16x32_bf16 v[4:7], v[214:217], v[206:209], v[4:7]
	v_mfma_f32_16x16x32_bf16 v[0:3], v[236:239], v[206:209], v[0:3]
	v_mfma_f32_16x16x32_bf16 v[48:51], v[232:235], v[164:167], v[48:51]
	v_mfma_f32_16x16x32_bf16 v[40:43], v[240:243], v[164:167], v[40:43]
	v_mfma_f32_16x16x32_bf16 v[32:35], v[232:235], v[172:175], v[32:35]
	v_mfma_f32_16x16x32_bf16 v[24:27], v[240:243], v[172:175], v[24:27]
	v_mfma_f32_16x16x32_bf16 v[16:19], v[232:235], v[202:205], v[16:19]
	v_mfma_f32_16x16x32_bf16 v[8:11], v[240:243], v[202:205], v[8:11]
	v_mfma_f32_16x16x32_bf16 v[4:7], v[232:235], v[210:213], v[4:7]
	v_mfma_f32_16x16x32_bf16 v[0:3], v[240:243], v[210:213], v[0:3]
	s_add_i32 s60, 0, 0x18000
	v_add_u32_e32 v156, s60, v141
	s_barrier
	ds_read_b128 v[144:147], v156
	ds_read_b128 v[148:151], v156 offset:1024
	ds_read_b128 v[152:155], v156 offset:2048
	ds_read_b128 v[156:159], v156 offset:3072
	s_add_u32 s20, s48, 0x40000
	s_addc_u32 s21, s49, 0
	s_mov_b32 m0, s15
	v_lshl_add_u64 v[214:215], s[20:21], 0, v[132:133]
	ds_read_b128 v[160:163], v143 offset:32768
	ds_read_b128 v[164:167], v143 offset:33792
	ds_read_b128 v[168:171], v143 offset:34816
	ds_read_b128 v[172:175], v143 offset:35840
	ds_read_b128 v[198:201], v143 offset:36864
	ds_read_b128 v[202:205], v143 offset:37888
	ds_read_b128 v[206:209], v143 offset:38912
	ds_read_b128 v[210:213], v143 offset:39936
	global_load_lds_dwordx4 v[214:215], off
	v_lshl_add_u64 v[214:215], s[20:21], 0, v[130:131]
	s_mov_b32 m0, s34
	s_nop 0
	global_load_lds_dwordx4 v[214:215], off
	s_waitcnt lgkmcnt(8)
	s_barrier
	s_waitcnt lgkmcnt(0)
	v_mfma_f32_16x16x32_bf16 v[124:127], v[144:147], v[160:163], v[124:127]
	v_mfma_f32_16x16x32_bf16 v[120:123], v[152:155], v[160:163], v[120:123]
	v_mfma_f32_16x16x32_bf16 v[116:119], v[144:147], v[168:171], v[116:119]
	v_mfma_f32_16x16x32_bf16 v[108:111], v[152:155], v[168:171], v[108:111]
	v_mfma_f32_16x16x32_bf16 v[100:103], v[144:147], v[198:201], v[100:103]
	v_mfma_f32_16x16x32_bf16 v[92:95], v[152:155], v[198:201], v[92:95]
	v_mfma_f32_16x16x32_bf16 v[80:83], v[144:147], v[206:209], v[80:83]
	v_mfma_f32_16x16x32_bf16 v[72:75], v[152:155], v[206:209], v[72:75]
	v_mfma_f32_16x16x32_bf16 v[124:127], v[148:151], v[164:167], v[124:127]
	v_mfma_f32_16x16x32_bf16 v[120:123], v[156:159], v[164:167], v[120:123]
	v_mfma_f32_16x16x32_bf16 v[116:119], v[148:151], v[172:175], v[116:119]
	v_mfma_f32_16x16x32_bf16 v[108:111], v[156:159], v[172:175], v[108:111]
	v_mfma_f32_16x16x32_bf16 v[100:103], v[148:151], v[202:205], v[100:103]
	v_mfma_f32_16x16x32_bf16 v[92:95], v[156:159], v[202:205], v[92:95]
	v_mfma_f32_16x16x32_bf16 v[80:83], v[148:151], v[210:213], v[80:83]
	v_mfma_f32_16x16x32_bf16 v[72:75], v[156:159], v[210:213], v[72:75]
	s_barrier
	s_add_i32 s48, 0, 0x1c000
	s_add_i32 s20, s60, s6
	v_add_u32_e32 v184, s48, v141
	v_lshl_add_u64 v[138:139], v[138:139], 0, s[52:53]
	s_mov_b32 m0, s20
	ds_read_b128 v[214:217], v184
	ds_read_b128 v[232:235], v184 offset:1024
	ds_read_b128 v[236:239], v184 offset:2048
	ds_read_b128 v[240:243], v184 offset:3072
	global_load_lds_dwordx4 v[138:139], off
	v_lshl_add_u64 v[138:139], v[218:219], 0, s[52:53]
	s_add_i32 m0, s20, 0x2000
	s_nop 0
	global_load_lds_dwordx4 v[138:139], off
	s_barrier
	s_waitcnt lgkmcnt(0)
	v_mfma_f32_16x16x32_bf16 v[112:115], v[214:217], v[160:163], v[112:115]
	v_mfma_f32_16x16x32_bf16 v[104:107], v[236:239], v[160:163], v[104:107]
	v_mfma_f32_16x16x32_bf16 v[96:99], v[214:217], v[168:171], v[96:99]
	v_mfma_f32_16x16x32_bf16 v[88:91], v[236:239], v[168:171], v[88:91]
	v_mfma_f32_16x16x32_bf16 v[84:87], v[214:217], v[198:201], v[84:87]
	v_mfma_f32_16x16x32_bf16 v[76:79], v[236:239], v[198:201], v[76:79]
	v_mfma_f32_16x16x32_bf16 v[68:71], v[214:217], v[206:209], v[68:71]
	v_mfma_f32_16x16x32_bf16 v[64:67], v[236:239], v[206:209], v[64:67]
	v_mfma_f32_16x16x32_bf16 v[112:115], v[232:235], v[164:167], v[112:115]
	v_mfma_f32_16x16x32_bf16 v[104:107], v[240:243], v[164:167], v[104:107]
	v_mfma_f32_16x16x32_bf16 v[96:99], v[232:235], v[172:175], v[96:99]
	v_mfma_f32_16x16x32_bf16 v[88:91], v[240:243], v[172:175], v[88:91]
	v_mfma_f32_16x16x32_bf16 v[84:87], v[232:235], v[202:205], v[84:87]
	v_mfma_f32_16x16x32_bf16 v[76:79], v[240:243], v[202:205], v[76:79]
	v_mfma_f32_16x16x32_bf16 v[68:71], v[232:235], v[210:213], v[68:71]
	v_mfma_f32_16x16x32_bf16 v[64:67], v[240:243], v[210:213], v[64:67]
	s_mov_b32 m0, s51
	v_lshl_add_u64 v[138:139], v[244:245], 0, s[52:53]
	s_barrier
	ds_read_b128 v[160:163], v143 offset:49152
	ds_read_b128 v[164:167], v143 offset:50176
	ds_read_b128 v[168:171], v143 offset:51200
	ds_read_b128 v[172:175], v143 offset:52224
	ds_read_b128 v[198:201], v143 offset:53248
	ds_read_b128 v[202:205], v143 offset:54272
	ds_read_b128 v[206:209], v143 offset:55296
	ds_read_b128 v[210:213], v143 offset:56320
	global_load_lds_dwordx4 v[138:139], off
	v_lshl_add_u64 v[138:139], v[246:247], 0, s[52:53]
	s_mov_b32 m0, s54
	s_nop 0
	global_load_lds_dwordx4 v[138:139], off
	s_barrier
	s_waitcnt lgkmcnt(0)
	v_mfma_f32_16x16x32_bf16 v[60:63], v[144:147], v[160:163], v[60:63]
	v_mfma_f32_16x16x32_bf16 v[56:59], v[152:155], v[160:163], v[56:59]
	v_mfma_f32_16x16x32_bf16 v[52:55], v[144:147], v[168:171], v[52:55]
	v_mfma_f32_16x16x32_bf16 v[44:47], v[152:155], v[168:171], v[44:47]
	v_mfma_f32_16x16x32_bf16 v[36:39], v[144:147], v[198:201], v[36:39]
	v_mfma_f32_16x16x32_bf16 v[28:31], v[152:155], v[198:201], v[28:31]
	v_mfma_f32_16x16x32_bf16 v[20:23], v[144:147], v[206:209], v[20:23]
	v_mfma_f32_16x16x32_bf16 v[12:15], v[152:155], v[206:209], v[12:15]
	v_mfma_f32_16x16x32_bf16 v[60:63], v[148:151], v[164:167], v[60:63]
	v_mfma_f32_16x16x32_bf16 v[56:59], v[156:159], v[164:167], v[56:59]
	v_mfma_f32_16x16x32_bf16 v[52:55], v[148:151], v[172:175], v[52:55]
	v_mfma_f32_16x16x32_bf16 v[44:47], v[156:159], v[172:175], v[44:47]
	v_mfma_f32_16x16x32_bf16 v[36:39], v[148:151], v[202:205], v[36:39]
	v_mfma_f32_16x16x32_bf16 v[28:31], v[156:159], v[202:205], v[28:31]
	v_mfma_f32_16x16x32_bf16 v[20:23], v[148:151], v[210:213], v[20:23]
	v_mfma_f32_16x16x32_bf16 v[12:15], v[156:159], v[210:213], v[12:15]
	s_barrier
	s_add_u32 s20, s28, 0x40080
	s_addc_u32 s21, s29, 0
	s_add_i32 s28, s48, s6
	v_lshl_add_u64 v[138:139], s[20:21], 0, v[176:177]
	s_mov_b32 m0, s28
	s_nop 0
	global_load_lds_dwordx4 v[138:139], off
	v_lshl_add_u64 v[138:139], s[20:21], 0, v[128:129]
	s_add_i32 m0, s28, 0x2000
	s_nop 0
	global_load_lds_dwordx4 v[138:139], off
	s_waitcnt vmcnt(6)
	s_barrier
	v_mfma_f32_16x16x32_bf16 v[48:51], v[214:217], v[160:163], v[48:51]
	v_mfma_f32_16x16x32_bf16 v[40:43], v[236:239], v[160:163], v[40:43]
	v_mfma_f32_16x16x32_bf16 v[32:35], v[214:217], v[168:171], v[32:35]
	v_mfma_f32_16x16x32_bf16 v[24:27], v[236:239], v[168:171], v[24:27]
	v_mfma_f32_16x16x32_bf16 v[16:19], v[214:217], v[198:201], v[16:19]
	v_mfma_f32_16x16x32_bf16 v[8:11], v[236:239], v[198:201], v[8:11]
	v_mfma_f32_16x16x32_bf16 v[4:7], v[214:217], v[206:209], v[4:7]
	v_mfma_f32_16x16x32_bf16 v[0:3], v[236:239], v[206:209], v[0:3]
	v_mfma_f32_16x16x32_bf16 v[48:51], v[232:235], v[164:167], v[48:51]
	v_mfma_f32_16x16x32_bf16 v[40:43], v[240:243], v[164:167], v[40:43]
	v_mfma_f32_16x16x32_bf16 v[32:35], v[232:235], v[172:175], v[32:35]
	v_mfma_f32_16x16x32_bf16 v[24:27], v[240:243], v[172:175], v[24:27]
	v_mfma_f32_16x16x32_bf16 v[16:19], v[232:235], v[202:205], v[16:19]
	v_mfma_f32_16x16x32_bf16 v[8:11], v[240:243], v[202:205], v[8:11]
	v_mfma_f32_16x16x32_bf16 v[4:7], v[232:235], v[210:213], v[4:7]
	v_mfma_f32_16x16x32_bf16 v[0:3], v[240:243], v[210:213], v[0:3]
	s_add_i32 vcc_lo, vcc_lo, 2
	s_add_u32 s46, s46, 0x100
	s_addc_u32 s47, s47, 0
	s_add_u32 s58, s58, 0x100
	s_addc_u32 s59, s59, 0
	s_cmp_gt_u32 vcc_lo, 13
	s_barrier
	s_cbranch_scc0 .LBB0_292
	v_lshl_add_u32 v144, s57, 8, v140
	v_lshl_or_b32 v138, s2, 8, v142
	v_ashrrev_i32_e32 v145, 31, v144
	v_readlane_b32 s20, v254, 43
	v_ashrrev_i32_e32 v139, 31, v138
	v_lshlrev_b64 v[146:147], 16, v[144:145]
	v_readlane_b32 s21, v254, 44
	v_lshlrev_b64 v[148:149], 1, v[138:139]
	v_cvt_pk_bf16_f32 v124, v124, v125
	v_cvt_pk_bf16_f32 v125, v126, v127
	v_cvt_pk_bf16_f32 v126, v120, v121
	v_cvt_pk_bf16_f32 v127, v122, v123
	s_nop 0
	v_lshl_add_u64 v[146:147], s[20:21], 0, v[146:147]
	v_lshl_add_u64 v[138:139], v[146:147], 0, v[148:149]
	global_store_dwordx4 v[138:139], v[124:127], off
	v_cvt_pk_bf16_f32 v112, v112, v113
	v_cvt_pk_bf16_f32 v113, v114, v115
	v_cvt_pk_bf16_f32 v114, v104, v105
	v_or_b32_e32 v104, 16, v144
	v_ashrrev_i32_e32 v105, 31, v104
	v_lshlrev_b64 v[104:105], 16, v[104:105]
	v_lshl_add_u64 v[104:105], s[20:21], 0, v[104:105]
	v_cvt_pk_bf16_f32 v115, v106, v107
	global_store_dwordx4 v[138:139], v[112:115], off offset:256
	s_mov_b32 s1, 0x900000
	s_mov_b32 s2, s0
	v_lshl_add_u64 v[112:113], v[104:105], 0, v[148:149]
	v_cvt_pk_bf16_f32 v104, v116, v117
	v_cvt_pk_bf16_f32 v105, v118, v119
	v_cvt_pk_bf16_f32 v106, v108, v109
	v_cvt_pk_bf16_f32 v107, v110, v111
	global_store_dwordx4 v[112:113], v[104:107], off
	v_cvt_pk_bf16_f32 v96, v96, v97
	v_cvt_pk_bf16_f32 v97, v98, v99
	v_cvt_pk_bf16_f32 v98, v88, v89
	v_or_b32_e32 v88, 32, v144
	v_ashrrev_i32_e32 v89, 31, v88
	v_lshlrev_b64 v[88:89], 16, v[88:89]
	v_lshl_add_u64 v[88:89], s[20:21], 0, v[88:89]
	v_cvt_pk_bf16_f32 v99, v90, v91
	global_store_dwordx4 v[112:113], v[96:99], off offset:256
	s_mov_b32 s57, s40
	s_mov_b64 s[28:29], s[44:45]
	v_lshl_add_u64 v[96:97], v[88:89], 0, v[148:149]
	v_cvt_pk_bf16_f32 v88, v100, v101
	v_cvt_pk_bf16_f32 v89, v102, v103
	v_cvt_pk_bf16_f32 v90, v92, v93
	v_cvt_pk_bf16_f32 v91, v94, v95
	global_store_dwordx4 v[96:97], v[88:91], off
	v_cvt_pk_bf16_f32 v84, v84, v85
	v_cvt_pk_bf16_f32 v85, v86, v87
	v_cvt_pk_bf16_f32 v86, v76, v77
	v_or_b32_e32 v76, 48, v144
	v_ashrrev_i32_e32 v77, 31, v76
	v_lshlrev_b64 v[76:77], 16, v[76:77]
	v_lshl_add_u64 v[76:77], s[20:21], 0, v[76:77]
	v_cvt_pk_bf16_f32 v87, v78, v79
	global_store_dwordx4 v[96:97], v[84:87], off offset:256
	s_mov_b64 s[20:21], 0x800000
	s_mov_b64 s[46:47], s[42:43]
	v_lshl_add_u64 v[84:85], v[76:77], 0, v[148:149]
	v_cvt_pk_bf16_f32 v76, v80, v81
	v_cvt_pk_bf16_f32 v77, v82, v83
	v_cvt_pk_bf16_f32 v78, v72, v73
	v_cvt_pk_bf16_f32 v79, v74, v75
	global_store_dwordx4 v[84:85], v[76:79], off
	v_cvt_pk_bf16_f32 v68, v68, v69
	v_cvt_pk_bf16_f32 v69, v70, v71
	v_cvt_pk_bf16_f32 v70, v64, v65
	v_cvt_pk_bf16_f32 v71, v66, v67
	global_store_dwordx4 v[84:85], v[68:71], off offset:256
	v_cvt_pk_bf16_f32 v60, v60, v61
	v_cvt_pk_bf16_f32 v61, v62, v63
	v_cvt_pk_bf16_f32 v62, v56, v57
	v_add_co_u32_e32 v56, vcc, s23, v138
	v_lshl_add_u64 v[64:65], v[138:139], 0, s[20:21]
	s_nop 0
	v_addc_co_u32_e32 v57, vcc, 0, v139, vcc
	v_cvt_pk_bf16_f32 v63, v58, v59
	global_store_dwordx4 v[56:57], v[60:63], off
	v_cvt_pk_bf16_f32 v48, v48, v49
	v_cvt_pk_bf16_f32 v49, v50, v51
	v_cvt_pk_bf16_f32 v50, v40, v41
	v_cvt_pk_bf16_f32 v51, v42, v43
	global_store_dwordx4 v[64:65], v[48:51], off offset:256
	s_mov_b64 s[20:21], 0x900000
	v_cvt_pk_bf16_f32 v40, v52, v53
	v_cvt_pk_bf16_f32 v41, v54, v55
	v_cvt_pk_bf16_f32 v42, v44, v45
	v_add_co_u32_e32 v44, vcc, s1, v138
	v_lshl_add_u64 v[48:49], v[138:139], 0, s[20:21]
	s_nop 0
	v_addc_co_u32_e32 v45, vcc, 0, v139, vcc
	s_mov_b32 s1, 0xa00000
	v_cvt_pk_bf16_f32 v43, v46, v47
	global_store_dwordx4 v[44:45], v[40:43], off
	v_cvt_pk_bf16_f32 v32, v32, v33
	v_cvt_pk_bf16_f32 v33, v34, v35
	v_cvt_pk_bf16_f32 v34, v24, v25
	v_cvt_pk_bf16_f32 v35, v26, v27
	global_store_dwordx4 v[48:49], v[32:35], off offset:256
	s_mov_b64 s[20:21], 0xa00000
	v_cvt_pk_bf16_f32 v24, v36, v37
	v_cvt_pk_bf16_f32 v25, v38, v39
	v_cvt_pk_bf16_f32 v26, v28, v29
	v_add_co_u32_e32 v28, vcc, s1, v138
	v_lshl_add_u64 v[32:33], v[138:139], 0, s[20:21]
	s_nop 0
	v_addc_co_u32_e32 v29, vcc, 0, v139, vcc
	s_mov_b32 s1, 0xb00000
	v_cvt_pk_bf16_f32 v27, v30, v31
	global_store_dwordx4 v[28:29], v[24:27], off
	v_cvt_pk_bf16_f32 v16, v16, v17
	v_cvt_pk_bf16_f32 v17, v18, v19
	v_cvt_pk_bf16_f32 v18, v8, v9
	v_cvt_pk_bf16_f32 v19, v10, v11
	global_store_dwordx4 v[32:33], v[16:19], off offset:256
	v_cvt_pk_bf16_f32 v8, v20, v21
	v_cvt_pk_bf16_f32 v9, v22, v23
	v_cvt_pk_bf16_f32 v10, v12, v13
	v_add_co_u32_e32 v12, vcc, s1, v138
	s_mov_b64 s[20:21], 0xb00000
	s_nop 0
	v_addc_co_u32_e32 v13, vcc, 0, v139, vcc
	v_lshl_add_u64 v[16:17], v[138:139], 0, s[20:21]
	s_and_b64 vcc, exec, s[38:39]
	v_cvt_pk_bf16_f32 v11, v14, v15
	global_store_dwordx4 v[12:13], v[8:11], off
	v_cvt_pk_bf16_f32 v4, v4, v5
	v_cvt_pk_bf16_f32 v5, v6, v7
	v_cvt_pk_bf16_f32 v6, v0, v1
	v_cvt_pk_bf16_f32 v7, v2, v3
	global_store_dwordx4 v[16:17], v[4:7], off offset:256
	s_cbranch_vccz .LBB0_285
	s_waitcnt vmcnt(0)
	v_readlane_b32 s54, v253, 37
	s_cmpk_gt_u32 s3, 0xff
	v_readlane_b32 s55, v253, 38
	s_cbranch_scc1 .LBB0_296
	s_barrier
